# all float a/b IEEE division sequences replaced by rcp+mul (f32, 1ulp) on top of routing+expert loop rewrite
# baseline (speedup 1.0000x reference)
.LBB0_145:
	global_load_dword v5, v[2:3], off
	v_add_u32_e32 v6, 0x100, v6
	v_cmp_lt_i32_e32 vcc, s28, v6
	s_or_b64 s[24:25], vcc, s[24:25]
	v_lshl_add_u64 v[2:3], v[2:3], 0, s[26:27]
	s_waitcnt vmcnt(0)
	v_mul_f32_e32 v7, 0xbfb8aa3b, v5
	v_exp_f32_e32 v7, v7
	s_nop 0
	v_add_f32_e32 v7, 1.0, v7
	v_rcp_f32_e32 v8, v7
	s_nop 0
	v_mul_f32_e32 v5, v5, v8
	ds_write_b32 v1, v5
	v_add_u32_e32 v1, 0x400, v1
	s_andn2_b64 exec, exec, s[24:25]
	s_cbranch_execnz .LBB0_145

.LBB0_869:
	ds_bpermute_b32 v1, v165, v202
	v_cndmask_b32_e64 v0, v162, v161, s[12:13]
	s_mov_b64 s[12:13], 0
	s_waitcnt lgkmcnt(0)
	v_add_f32_e32 v1, v202, v1
	v_rcp_f32_e32 v2, v1
	s_nop 0
	v_cmp_lt_f32_e64 s[0:1], 0, v1
	v_mul_f32_e32 v0, v0, v2
	v_cndmask_b32_e64 v0, 0, v0, s[0:1]
	v_lshlrev_b32_e32 v2, 16, v172
	v_and_b32_e32 v3, 0xffff0000, v172
	v_pk_fma_f32 v[2:3], v[64:65], v[0:1], v[2:3] op_sel_hi:[1,0,1]
	s_mov_b64 s[0:1], 0x1000000
	v_cvt_pk_bf16_f32 v172, v2, v3
	v_lshlrev_b32_e32 v2, 16, v173
	v_and_b32_e32 v3, 0xffff0000, v173
	v_pk_fma_f32 v[2:3], v[66:67], v[0:1], v[2:3] op_sel_hi:[1,0,1]
	s_and_b64 vcc, s[10:11], exec
	v_cvt_pk_bf16_f32 v173, v2, v3
	v_lshlrev_b32_e32 v2, 16, v174
	v_and_b32_e32 v3, 0xffff0000, v174
	v_pk_fma_f32 v[2:3], v[68:69], v[0:1], v[2:3] op_sel_hi:[1,0,1]
	s_nop 0
	v_cvt_pk_bf16_f32 v174, v2, v3
	v_lshlrev_b32_e32 v2, 16, v175
	v_and_b32_e32 v3, 0xffff0000, v175
	v_pk_fma_f32 v[2:3], v[70:71], v[0:1], v[2:3] op_sel_hi:[1,0,1]
	s_nop 0
	v_cvt_pk_bf16_f32 v175, v2, v3
	v_lshlrev_b32_e32 v2, 16, v176
	v_and_b32_e32 v3, 0xffff0000, v176
	v_pk_fma_f32 v[2:3], v[72:73], v[0:1], v[2:3] op_sel_hi:[1,0,1]
	s_nop 0
	v_cvt_pk_bf16_f32 v176, v2, v3
	v_lshlrev_b32_e32 v2, 16, v177
	v_and_b32_e32 v3, 0xffff0000, v177
	v_pk_fma_f32 v[2:3], v[74:75], v[0:1], v[2:3] op_sel_hi:[1,0,1]
	s_nop 0
	v_cvt_pk_bf16_f32 v177, v2, v3
	v_lshlrev_b32_e32 v2, 16, v178
	v_and_b32_e32 v3, 0xffff0000, v178
	v_pk_fma_f32 v[2:3], v[76:77], v[0:1], v[2:3] op_sel_hi:[1,0,1]
	s_nop 0
	v_cvt_pk_bf16_f32 v178, v2, v3
	v_lshlrev_b32_e32 v2, 16, v179
	v_and_b32_e32 v3, 0xffff0000, v179
	v_pk_fma_f32 v[2:3], v[78:79], v[0:1], v[2:3] op_sel_hi:[1,0,1]
	s_nop 0
	v_cvt_pk_bf16_f32 v179, v2, v3
	v_lshlrev_b32_e32 v2, 16, v180
	v_and_b32_e32 v3, 0xffff0000, v180
	v_pk_fma_f32 v[2:3], v[48:49], v[0:1], v[2:3] op_sel_hi:[1,0,1]
	s_nop 0
	v_cvt_pk_bf16_f32 v180, v2, v3
	v_lshlrev_b32_e32 v2, 16, v181
	v_and_b32_e32 v3, 0xffff0000, v181
	v_pk_fma_f32 v[2:3], v[50:51], v[0:1], v[2:3] op_sel_hi:[1,0,1]
	s_nop 0
	v_cvt_pk_bf16_f32 v181, v2, v3
	v_lshlrev_b32_e32 v2, 16, v182
	v_and_b32_e32 v3, 0xffff0000, v182
	v_pk_fma_f32 v[2:3], v[52:53], v[0:1], v[2:3] op_sel_hi:[1,0,1]
	s_nop 0
	v_cvt_pk_bf16_f32 v182, v2, v3
	v_lshlrev_b32_e32 v2, 16, v183
	v_and_b32_e32 v3, 0xffff0000, v183
	v_pk_fma_f32 v[2:3], v[54:55], v[0:1], v[2:3] op_sel_hi:[1,0,1]
	s_nop 0
	v_cvt_pk_bf16_f32 v183, v2, v3
	v_lshlrev_b32_e32 v2, 16, v186
	v_and_b32_e32 v3, 0xffff0000, v186
	v_pk_fma_f32 v[2:3], v[56:57], v[0:1], v[2:3] op_sel_hi:[1,0,1]
	s_nop 0
	v_cvt_pk_bf16_f32 v186, v2, v3
	v_lshlrev_b32_e32 v2, 16, v187
	v_and_b32_e32 v3, 0xffff0000, v187
	v_pk_fma_f32 v[2:3], v[58:59], v[0:1], v[2:3] op_sel_hi:[1,0,1]
	s_nop 0
	v_cvt_pk_bf16_f32 v187, v2, v3
	v_lshlrev_b32_e32 v2, 16, v184
	v_and_b32_e32 v3, 0xffff0000, v184
	v_pk_fma_f32 v[2:3], v[60:61], v[0:1], v[2:3] op_sel_hi:[1,0,1]
	s_nop 0
	v_cvt_pk_bf16_f32 v184, v2, v3
	v_lshlrev_b32_e32 v2, 16, v185
	v_and_b32_e32 v3, 0xffff0000, v185
	v_pk_fma_f32 v[0:1], v[62:63], v[0:1], v[2:3] op_sel_hi:[1,0,1]
	s_nop 0
	v_cvt_pk_bf16_f32 v185, v0, v1
	s_cbranch_vccnz .LBB0_781
	s_mov_b64 s[10:11], -1
	s_branch .LBB0_850

.LBB0_1018:
	s_add_i32 s3, s1, 1
	s_cmp_lt_u32 s1, 15
	s_cselect_b32 s1, s3, s1
	s_lshl_b32 s12, s1, 6
	s_lshl_b64 s[10:11], s[12:13], 1
	s_barrier
	s_waitcnt vmcnt(0)
	ds_write_b128 v204, v[174:177]
	ds_write_b128 v204, v[170:173] offset:4608
	ds_write_b128 v204, v[166:169] offset:9216
	ds_write_b128 v204, v[162:165] offset:13824
	ds_write_b128 v204, v[158:161] offset:18432
	ds_write_b128 v204, v[154:157] offset:23040
	ds_write_b128 v204, v[150:153] offset:27648
	ds_write_b128 v204, v[146:149] offset:32256
	ds_write_b128 v204, v[142:145] offset:36864
	ds_write_b128 v204, v[134:137] offset:41472
	ds_write_b128 v204, v[130:133] offset:46080
	ds_write_b128 v204, v[138:141] offset:50688
	v_lshl_add_u64 v[130:131], v[178:179], 0, s[10:11]
	v_lshl_add_u64 v[132:133], v[184:185], 0, s[10:11]
	v_lshl_add_u64 v[134:135], v[186:187], 0, s[10:11]
	v_lshl_add_u64 v[136:137], v[188:189], 0, s[10:11]
	v_lshl_add_u64 v[138:139], v[190:191], 0, s[10:11]
	v_lshl_add_u64 v[140:141], v[192:193], 0, s[10:11]
	v_lshl_add_u64 v[142:143], v[194:195], 0, s[10:11]
	v_lshl_add_u64 v[144:145], v[196:197], 0, s[10:11]
	s_waitcnt lgkmcnt(0)
	s_barrier
	v_lshl_add_u64 v[224:225], v[180:181], 0, s[10:11]
	v_lshl_add_u64 v[226:227], v[198:199], 0, s[10:11]
	v_lshl_add_u64 v[228:229], v[200:201], 0, s[10:11]
	v_lshl_add_u64 v[230:231], v[202:203], 0, s[10:11]
	global_load_dwordx4 v[174:177], v[130:131], off
	global_load_dwordx4 v[170:173], v[132:133], off
	global_load_dwordx4 v[166:169], v[134:135], off
	global_load_dwordx4 v[162:165], v[136:137], off
	global_load_dwordx4 v[158:161], v[138:139], off
	global_load_dwordx4 v[154:157], v[140:141], off
	global_load_dwordx4 v[150:153], v[142:143], off
	global_load_dwordx4 v[146:149], v[144:145], off
	s_nop 0
	global_load_dwordx4 v[142:145], v[224:225], off
	global_load_dwordx4 v[134:137], v[226:227], off
	global_load_dwordx4 v[130:133], v[228:229], off
	global_load_dwordx4 v[138:141], v[230:231], off
	ds_read_b128 v[224:227], v182
	ds_read_b128 v[228:231], v183 offset:36864
	ds_read_b128 v[232:235], v183 offset:41472
	ds_read_b128 v[236:239], v183 offset:46080
	ds_read_b128 v[240:243], v183 offset:50688
	s_cmp_lg_u32 s3, 16
	s_waitcnt lgkmcnt(3)
	v_mfma_f32_32x32x16_bf16 v[114:129], v[224:227], v[228:231], v[114:129]
	s_mov_b32 s1, s3
	s_waitcnt lgkmcnt(2)
	v_mfma_f32_32x32x16_bf16 v[82:97], v[224:227], v[232:235], v[82:97]
	s_waitcnt lgkmcnt(1)
	v_mfma_f32_32x32x16_bf16 v[98:113], v[224:227], v[236:239], v[98:113]
	s_waitcnt lgkmcnt(0)
	v_mfma_f32_32x32x16_bf16 v[66:81], v[224:227], v[240:243], v[66:81]
	ds_read_b128 v[224:227], v182 offset:4608
	s_waitcnt lgkmcnt(0)
	v_mfma_f32_32x32x16_bf16 v[50:65], v[224:227], v[228:231], v[50:65]
	v_mfma_f32_32x32x16_bf16 v[16:31], v[224:227], v[232:235], v[16:31]
	v_mfma_f32_32x32x16_bf16 v[34:49], v[224:227], v[236:239], v[34:49]
	v_mfma_f32_32x32x16_bf16 v[0:15], v[224:227], v[240:243], v[0:15]
	ds_read_b128 v[224:227], v182 offset:32
	ds_read_b128 v[228:231], v183 offset:36896
	ds_read_b128 v[232:235], v183 offset:41504
	ds_read_b128 v[236:239], v183 offset:46112
	ds_read_b128 v[240:243], v183 offset:50720
	s_waitcnt lgkmcnt(3)
	v_mfma_f32_32x32x16_bf16 v[114:129], v[224:227], v[228:231], v[114:129]
	s_waitcnt lgkmcnt(2)
	v_mfma_f32_32x32x16_bf16 v[82:97], v[224:227], v[232:235], v[82:97]
	s_waitcnt lgkmcnt(1)
	v_mfma_f32_32x32x16_bf16 v[98:113], v[224:227], v[236:239], v[98:113]
	s_waitcnt lgkmcnt(0)
	v_mfma_f32_32x32x16_bf16 v[66:81], v[224:227], v[240:243], v[66:81]
	ds_read_b128 v[224:227], v182 offset:4640
	s_waitcnt lgkmcnt(0)
	v_mfma_f32_32x32x16_bf16 v[50:65], v[224:227], v[228:231], v[50:65]
	v_mfma_f32_32x32x16_bf16 v[16:31], v[224:227], v[232:235], v[16:31]
	v_mfma_f32_32x32x16_bf16 v[34:49], v[224:227], v[236:239], v[34:49]
	v_mfma_f32_32x32x16_bf16 v[0:15], v[224:227], v[240:243], v[0:15]
	ds_read_b128 v[224:227], v182 offset:64
	ds_read_b128 v[228:231], v183 offset:36928
	ds_read_b128 v[232:235], v183 offset:41536
	ds_read_b128 v[236:239], v183 offset:46144
	ds_read_b128 v[240:243], v183 offset:50752
	s_waitcnt lgkmcnt(3)
	v_mfma_f32_32x32x16_bf16 v[114:129], v[224:227], v[228:231], v[114:129]
	s_waitcnt lgkmcnt(2)
	v_mfma_f32_32x32x16_bf16 v[82:97], v[224:227], v[232:235], v[82:97]
	s_waitcnt lgkmcnt(1)
	v_mfma_f32_32x32x16_bf16 v[98:113], v[224:227], v[236:239], v[98:113]
	s_waitcnt lgkmcnt(0)
	v_mfma_f32_32x32x16_bf16 v[66:81], v[224:227], v[240:243], v[66:81]
	ds_read_b128 v[224:227], v182 offset:4672
	s_waitcnt lgkmcnt(0)
	v_mfma_f32_32x32x16_bf16 v[50:65], v[224:227], v[228:231], v[50:65]
	v_mfma_f32_32x32x16_bf16 v[16:31], v[224:227], v[232:235], v[16:31]
	v_mfma_f32_32x32x16_bf16 v[34:49], v[224:227], v[236:239], v[34:49]
	v_mfma_f32_32x32x16_bf16 v[0:15], v[224:227], v[240:243], v[0:15]
	ds_read_b128 v[224:227], v182 offset:96
	ds_read_b128 v[228:231], v183 offset:36960
	ds_read_b128 v[232:235], v183 offset:41568
	ds_read_b128 v[236:239], v183 offset:46176
	ds_read_b128 v[240:243], v183 offset:50784
	s_waitcnt lgkmcnt(3)
	v_mfma_f32_32x32x16_bf16 v[114:129], v[224:227], v[228:231], v[114:129]
	s_waitcnt lgkmcnt(2)
	v_mfma_f32_32x32x16_bf16 v[82:97], v[224:227], v[232:235], v[82:97]
	s_waitcnt lgkmcnt(1)
	v_mfma_f32_32x32x16_bf16 v[98:113], v[224:227], v[236:239], v[98:113]
	s_waitcnt lgkmcnt(0)
	v_mfma_f32_32x32x16_bf16 v[66:81], v[224:227], v[240:243], v[66:81]
	ds_read_b128 v[224:227], v182 offset:4704
	s_waitcnt lgkmcnt(0)
	v_mfma_f32_32x32x16_bf16 v[50:65], v[224:227], v[228:231], v[50:65]
	v_mfma_f32_32x32x16_bf16 v[16:31], v[224:227], v[232:235], v[16:31]
	v_mfma_f32_32x32x16_bf16 v[34:49], v[224:227], v[236:239], v[34:49]
	v_mfma_f32_32x32x16_bf16 v[0:15], v[224:227], v[240:243], v[0:15]
	s_cbranch_scc1 .LBB0_1018
	s_lshl_b32 s1, s2, 8
	s_bfe_i32 s2, s2, 0x10017
	s_lshr_b32 s2, s2, 19
	v_writelane_b32 v251, s12, 29
	s_add_i32 s2, s1, s2
	s_and_b32 s2, s2, 0xffffe000
	v_writelane_b32 v251, s13, 30
	s_ashr_i32 s12, s8, 8
	s_add_i32 s12, s12, s9
	s_sub_i32 s17, s1, s2
	s_cmp_gt_i32 s0, 15
	s_mov_b64 s[2:3], -1
	s_barrier
	s_cbranch_scc0 .LBB0_1025
	s_cmp_gt_u32 s0, 31
	s_cbranch_scc0 .LBB0_1022
	v_mov_b32_e32 v32, v206
	v_readlane_b32 s24, v249, 18
	s_waitcnt vmcnt(1)
	v_and_b32_e32 v130, 0xffffffc0, v32
	v_lshrrev_b32_e32 v131, 3, v32
	v_and_or_b32 v130, v131, 4, v130
	v_add_u32_e32 v132, s1, v130
	s_lshl_b32 s1, s0, 8
	v_readlane_b32 s26, v249, 20
	v_and_b32_e32 v32, 31, v32
	v_readlane_b32 s27, v249, 21
	s_add_u32 s2, s26, s1
	s_addc_u32 s3, s27, 0
	v_lshlrev_b32_e32 v32, 1, v32
	v_lshl_add_u64 v[130:131], s[2:3], 0, v[32:33]
	v_mul_f32_e32 v32, 0xbfb8aa3b, v114
	v_exp_f32_e32 v32, v32
	s_movk_i32 s2, 0xe000
	s_mov_b32 s3, -1
	v_lshl_add_u64 v[130:131], v[130:131], 0, s[2:3]
	v_add_f32_e32 v32, 1.0, v32
	v_rcp_f32_e32 v134, v32
	s_nop 0
	v_ashrrev_i32_e32 v133, 31, v132
	s_movk_i32 s1, 0x7fff
	v_readlane_b32 s25, v249, 19
	s_waitcnt vmcnt(0)
	v_mul_f32_e32 v32, v114, v134
	v_bfe_u32 v134, v32, 16, 1
	v_add3_u32 v32, v32, v134, s1
	v_lshlrev_b64 v[134:135], 12, v[132:133]
	v_lshl_add_u64 v[134:135], v[130:131], 0, v[134:135]
	global_store_short_d16_hi v[134:135], v32, off
	v_mul_f32_e32 v32, 0xbfb8aa3b, v98
	v_exp_f32_e32 v32, v32
	v_readlane_b32 s28, v249, 22
	v_readlane_b32 s29, v249, 23
	v_readlane_b32 s30, v249, 24
	v_add_f32_e32 v32, 1.0, v32
	v_rcp_f32_e32 v133, v32
	s_nop 0
	v_readlane_b32 s31, v249, 25
	v_mul_f32_e32 v32, v98, v133
	v_bfe_u32 v133, v32, 16, 1
	v_add3_u32 v32, v32, v133, s1
	global_store_short_d16_hi v[134:135], v32, off offset:128
	v_mul_f32_e32 v32, 0xbfb8aa3b, v115
	v_exp_f32_e32 v32, v32
	v_or_b32_e32 v136, 1, v132
	v_ashrrev_i32_e32 v137, 31, v136
	v_lshlrev_b64 v[136:137], 12, v[136:137]
	v_add_f32_e32 v32, 1.0, v32
	v_rcp_f32_e32 v133, v32
	s_nop 0
	v_lshl_add_u64 v[136:137], v[130:131], 0, v[136:137]
	v_mul_f32_e32 v32, v115, v133
	v_bfe_u32 v133, v32, 16, 1
	v_add3_u32 v32, v32, v133, s1
	global_store_short_d16_hi v[136:137], v32, off
	v_mul_f32_e32 v32, 0xbfb8aa3b, v99
	v_exp_f32_e32 v32, v32
	s_nop 0
	v_add_f32_e32 v32, 1.0, v32
	v_rcp_f32_e32 v133, v32
	s_nop 0
	v_mul_f32_e32 v32, v99, v133
	v_bfe_u32 v133, v32, 16, 1
	v_add3_u32 v32, v32, v133, s1
	global_store_short_d16_hi v[136:137], v32, off offset:128
	v_mul_f32_e32 v32, 0xbfb8aa3b, v116
	v_exp_f32_e32 v32, v32
	v_or_b32_e32 v138, 2, v132
	v_ashrrev_i32_e32 v139, 31, v138
	v_lshlrev_b64 v[138:139], 12, v[138:139]
	v_add_f32_e32 v32, 1.0, v32
	v_rcp_f32_e32 v133, v32
	s_nop 0
	v_lshl_add_u64 v[138:139], v[130:131], 0, v[138:139]
	v_mul_f32_e32 v32, v116, v133
	v_bfe_u32 v133, v32, 16, 1
	v_add3_u32 v32, v32, v133, s1
	global_store_short_d16_hi v[138:139], v32, off
	v_mul_f32_e32 v32, 0xbfb8aa3b, v100
	v_exp_f32_e32 v32, v32
	s_nop 0
	v_add_f32_e32 v32, 1.0, v32
	v_rcp_f32_e32 v133, v32
	s_nop 0
	v_mul_f32_e32 v32, v100, v133
	v_bfe_u32 v133, v32, 16, 1
	v_add3_u32 v32, v32, v133, s1
	global_store_short_d16_hi v[138:139], v32, off offset:128
	v_mul_f32_e32 v32, 0xbfb8aa3b, v117
	v_exp_f32_e32 v32, v32
	v_or_b32_e32 v140, 3, v132
	v_ashrrev_i32_e32 v141, 31, v140
	v_lshlrev_b64 v[140:141], 12, v[140:141]
	v_add_f32_e32 v32, 1.0, v32
	v_rcp_f32_e32 v133, v32
	s_nop 0
	v_lshl_add_u64 v[140:141], v[130:131], 0, v[140:141]
	v_mul_f32_e32 v32, v117, v133
	v_bfe_u32 v133, v32, 16, 1
	v_add3_u32 v32, v32, v133, s1
	global_store_short_d16_hi v[140:141], v32, off
	v_mul_f32_e32 v32, 0xbfb8aa3b, v101
	v_exp_f32_e32 v32, v32
	s_nop 0
	v_add_f32_e32 v32, 1.0, v32
	v_rcp_f32_e32 v133, v32
	s_nop 0
	v_mul_f32_e32 v32, v101, v133
	v_bfe_u32 v133, v32, 16, 1
	v_add3_u32 v32, v32, v133, s1
	global_store_short_d16_hi v[140:141], v32, off offset:128
	v_mul_f32_e32 v32, 0xbfb8aa3b, v118
	v_exp_f32_e32 v32, v32
	v_or_b32_e32 v142, 8, v132
	v_ashrrev_i32_e32 v143, 31, v142
	v_lshlrev_b64 v[142:143], 12, v[142:143]
	v_add_f32_e32 v32, 1.0, v32
	v_rcp_f32_e32 v133, v32
	s_nop 0
	v_lshl_add_u64 v[142:143], v[130:131], 0, v[142:143]
	v_mul_f32_e32 v32, v118, v133
	v_bfe_u32 v133, v32, 16, 1
	v_add3_u32 v32, v32, v133, s1
	global_store_short_d16_hi v[142:143], v32, off
	v_mul_f32_e32 v32, 0xbfb8aa3b, v102
	v_exp_f32_e32 v32, v32
	s_nop 0
	v_add_f32_e32 v32, 1.0, v32
	v_rcp_f32_e32 v133, v32
	s_nop 0
	v_mul_f32_e32 v32, v102, v133
	v_bfe_u32 v133, v32, 16, 1
	v_add3_u32 v32, v32, v133, s1
	global_store_short_d16_hi v[142:143], v32, off offset:128
	v_mul_f32_e32 v32, 0xbfb8aa3b, v119
	v_exp_f32_e32 v32, v32
	v_or_b32_e32 v144, 9, v132
	v_ashrrev_i32_e32 v145, 31, v144
	v_lshlrev_b64 v[144:145], 12, v[144:145]
	v_add_f32_e32 v32, 1.0, v32
	v_rcp_f32_e32 v133, v32
	s_nop 0
	v_lshl_add_u64 v[144:145], v[130:131], 0, v[144:145]
	v_mul_f32_e32 v32, v119, v133
	v_bfe_u32 v133, v32, 16, 1
	v_add3_u32 v32, v32, v133, s1
	global_store_short_d16_hi v[144:145], v32, off
	v_mul_f32_e32 v32, 0xbfb8aa3b, v103
	v_exp_f32_e32 v32, v32
	s_nop 0
	v_add_f32_e32 v32, 1.0, v32
	v_rcp_f32_e32 v133, v32
	s_nop 0
	v_mul_f32_e32 v32, v103, v133
	v_bfe_u32 v133, v32, 16, 1
	v_add3_u32 v32, v32, v133, s1
	global_store_short_d16_hi v[144:145], v32, off offset:128
	v_mul_f32_e32 v32, 0xbfb8aa3b, v120
	v_exp_f32_e32 v32, v32
	v_or_b32_e32 v146, 10, v132
	v_ashrrev_i32_e32 v147, 31, v146
	v_lshlrev_b64 v[146:147], 12, v[146:147]
	v_add_f32_e32 v32, 1.0, v32
	v_rcp_f32_e32 v133, v32
	s_nop 0
	v_lshl_add_u64 v[146:147], v[130:131], 0, v[146:147]
	v_mul_f32_e32 v32, v120, v133
	v_bfe_u32 v133, v32, 16, 1
	v_add3_u32 v32, v32, v133, s1
	global_store_short_d16_hi v[146:147], v32, off
	v_mul_f32_e32 v32, 0xbfb8aa3b, v104
	v_exp_f32_e32 v32, v32
	s_nop 0
	v_add_f32_e32 v32, 1.0, v32
	v_rcp_f32_e32 v133, v32
	s_nop 0
	v_mul_f32_e32 v32, v104, v133
	v_bfe_u32 v133, v32, 16, 1
	v_add3_u32 v32, v32, v133, s1
	global_store_short_d16_hi v[146:147], v32, off offset:128
	v_mul_f32_e32 v32, 0xbfb8aa3b, v121
	v_exp_f32_e32 v32, v32
	v_or_b32_e32 v148, 11, v132
	v_ashrrev_i32_e32 v149, 31, v148
	v_lshlrev_b64 v[148:149], 12, v[148:149]
	v_add_f32_e32 v32, 1.0, v32
	v_rcp_f32_e32 v133, v32
	s_nop 0
	v_lshl_add_u64 v[148:149], v[130:131], 0, v[148:149]
	v_mul_f32_e32 v32, v121, v133
	v_bfe_u32 v133, v32, 16, 1
	v_add3_u32 v32, v32, v133, s1
	global_store_short_d16_hi v[148:149], v32, off
	v_mul_f32_e32 v32, 0xbfb8aa3b, v105
	v_exp_f32_e32 v32, v32
	s_nop 0
	v_add_f32_e32 v32, 1.0, v32
	v_rcp_f32_e32 v133, v32
	s_nop 0
	v_mul_f32_e32 v32, v105, v133
	v_bfe_u32 v133, v32, 16, 1
	v_add3_u32 v32, v32, v133, s1
	global_store_short_d16_hi v[148:149], v32, off offset:128
	v_mul_f32_e32 v32, 0xbfb8aa3b, v122
	v_exp_f32_e32 v32, v32
	v_or_b32_e32 v150, 16, v132
	v_ashrrev_i32_e32 v151, 31, v150
	v_lshlrev_b64 v[150:151], 12, v[150:151]
	v_add_f32_e32 v32, 1.0, v32
	v_rcp_f32_e32 v133, v32
	s_nop 0
	v_lshl_add_u64 v[150:151], v[130:131], 0, v[150:151]
	v_mul_f32_e32 v32, v122, v133
	v_bfe_u32 v133, v32, 16, 1
	v_add3_u32 v32, v32, v133, s1
	global_store_short_d16_hi v[150:151], v32, off
	v_mul_f32_e32 v32, 0xbfb8aa3b, v106
	v_exp_f32_e32 v32, v32
	s_nop 0
	v_add_f32_e32 v32, 1.0, v32
	v_rcp_f32_e32 v133, v32
	s_nop 0
	v_mul_f32_e32 v32, v106, v133
	v_bfe_u32 v133, v32, 16, 1
	v_add3_u32 v32, v32, v133, s1
	global_store_short_d16_hi v[150:151], v32, off offset:128
	v_mul_f32_e32 v32, 0xbfb8aa3b, v123
	v_exp_f32_e32 v32, v32
	v_or_b32_e32 v152, 17, v132
	v_ashrrev_i32_e32 v153, 31, v152
	v_lshlrev_b64 v[152:153], 12, v[152:153]
	v_add_f32_e32 v32, 1.0, v32
	v_rcp_f32_e32 v133, v32
	s_nop 0
	v_lshl_add_u64 v[152:153], v[130:131], 0, v[152:153]
	v_mul_f32_e32 v32, v123, v133
	v_bfe_u32 v133, v32, 16, 1
	v_add3_u32 v32, v32, v133, s1
	global_store_short_d16_hi v[152:153], v32, off
	v_mul_f32_e32 v32, 0xbfb8aa3b, v107
	v_exp_f32_e32 v32, v32
	s_nop 0
	v_add_f32_e32 v32, 1.0, v32
	v_rcp_f32_e32 v133, v32
	s_nop 0
	v_mul_f32_e32 v32, v107, v133
	v_bfe_u32 v133, v32, 16, 1
	v_add3_u32 v32, v32, v133, s1
	global_store_short_d16_hi v[152:153], v32, off offset:128
	v_mul_f32_e32 v32, 0xbfb8aa3b, v124
	v_exp_f32_e32 v32, v32
	v_or_b32_e32 v154, 18, v132
	v_ashrrev_i32_e32 v155, 31, v154
	v_lshlrev_b64 v[154:155], 12, v[154:155]
	v_add_f32_e32 v32, 1.0, v32
	v_rcp_f32_e32 v133, v32
	s_nop 0
	v_lshl_add_u64 v[154:155], v[130:131], 0, v[154:155]
	v_mul_f32_e32 v32, v124, v133
	v_bfe_u32 v133, v32, 16, 1
	v_add3_u32 v32, v32, v133, s1
	global_store_short_d16_hi v[154:155], v32, off
	v_mul_f32_e32 v32, 0xbfb8aa3b, v108
	v_exp_f32_e32 v32, v32
	s_nop 0
	v_add_f32_e32 v32, 1.0, v32
	v_rcp_f32_e32 v133, v32
	s_nop 0
	v_mul_f32_e32 v32, v108, v133
	v_bfe_u32 v133, v32, 16, 1
	v_add3_u32 v32, v32, v133, s1
	global_store_short_d16_hi v[154:155], v32, off offset:128
	v_mul_f32_e32 v32, 0xbfb8aa3b, v125
	v_exp_f32_e32 v32, v32
	v_or_b32_e32 v156, 19, v132
	v_ashrrev_i32_e32 v157, 31, v156
	v_lshlrev_b64 v[156:157], 12, v[156:157]
	v_add_f32_e32 v32, 1.0, v32
	v_rcp_f32_e32 v133, v32
	s_nop 0
	v_lshl_add_u64 v[156:157], v[130:131], 0, v[156:157]
	v_mul_f32_e32 v32, v125, v133
	v_bfe_u32 v133, v32, 16, 1
	v_add3_u32 v32, v32, v133, s1
	global_store_short_d16_hi v[156:157], v32, off
	v_mul_f32_e32 v32, 0xbfb8aa3b, v109
	v_exp_f32_e32 v32, v32
	s_nop 0
	v_add_f32_e32 v32, 1.0, v32
	v_rcp_f32_e32 v133, v32
	s_nop 0
	v_mul_f32_e32 v32, v109, v133
	v_bfe_u32 v133, v32, 16, 1
	v_add3_u32 v32, v32, v133, s1
	global_store_short_d16_hi v[156:157], v32, off offset:128
	v_mul_f32_e32 v32, 0xbfb8aa3b, v126
	v_exp_f32_e32 v32, v32
	v_or_b32_e32 v158, 24, v132
	v_ashrrev_i32_e32 v159, 31, v158
	v_lshlrev_b64 v[158:159], 12, v[158:159]
	v_add_f32_e32 v32, 1.0, v32
	v_rcp_f32_e32 v133, v32
	s_nop 0
	v_lshl_add_u64 v[158:159], v[130:131], 0, v[158:159]
	v_mul_f32_e32 v32, v126, v133
	v_bfe_u32 v133, v32, 16, 1
	v_add3_u32 v32, v32, v133, s1
	global_store_short_d16_hi v[158:159], v32, off
	v_mul_f32_e32 v32, 0xbfb8aa3b, v110
	v_exp_f32_e32 v32, v32
	s_nop 0
	v_add_f32_e32 v32, 1.0, v32
	v_rcp_f32_e32 v133, v32
	s_nop 0
	v_mul_f32_e32 v32, v110, v133
	v_bfe_u32 v133, v32, 16, 1
	v_add3_u32 v32, v32, v133, s1
	global_store_short_d16_hi v[158:159], v32, off offset:128
	v_mul_f32_e32 v32, 0xbfb8aa3b, v127
	v_exp_f32_e32 v32, v32
	v_or_b32_e32 v160, 25, v132
	v_ashrrev_i32_e32 v161, 31, v160
	v_lshlrev_b64 v[160:161], 12, v[160:161]
	v_add_f32_e32 v32, 1.0, v32
	v_rcp_f32_e32 v133, v32
	s_nop 0
	v_lshl_add_u64 v[160:161], v[130:131], 0, v[160:161]
	v_mul_f32_e32 v32, v127, v133
	v_bfe_u32 v133, v32, 16, 1
	v_add3_u32 v32, v32, v133, s1
	global_store_short_d16_hi v[160:161], v32, off
	v_mul_f32_e32 v32, 0xbfb8aa3b, v111
	v_exp_f32_e32 v32, v32
	s_nop 0
	v_add_f32_e32 v32, 1.0, v32
	v_rcp_f32_e32 v133, v32
	s_nop 0
	v_mul_f32_e32 v32, v111, v133
	v_bfe_u32 v133, v32, 16, 1
	v_add3_u32 v32, v32, v133, s1
	global_store_short_d16_hi v[160:161], v32, off offset:128
	v_mul_f32_e32 v32, 0xbfb8aa3b, v128
	v_exp_f32_e32 v32, v32
	v_or_b32_e32 v162, 26, v132
	v_ashrrev_i32_e32 v163, 31, v162
	v_lshlrev_b64 v[162:163], 12, v[162:163]
	v_add_f32_e32 v32, 1.0, v32
	v_rcp_f32_e32 v133, v32
	s_nop 0
	v_lshl_add_u64 v[162:163], v[130:131], 0, v[162:163]
	v_mul_f32_e32 v32, v128, v133
	v_bfe_u32 v133, v32, 16, 1
	v_add3_u32 v32, v32, v133, s1
	global_store_short_d16_hi v[162:163], v32, off
	v_mul_f32_e32 v32, 0xbfb8aa3b, v112
	v_exp_f32_e32 v32, v32
	s_nop 0
	v_add_f32_e32 v32, 1.0, v32
	v_rcp_f32_e32 v133, v32
	s_nop 0
	v_mul_f32_e32 v32, v112, v133
	v_bfe_u32 v133, v32, 16, 1
	v_add3_u32 v32, v32, v133, s1
	global_store_short_d16_hi v[162:163], v32, off offset:128
	v_mul_f32_e32 v32, 0xbfb8aa3b, v129
	v_exp_f32_e32 v32, v32
	v_or_b32_e32 v164, 27, v132
	v_ashrrev_i32_e32 v165, 31, v164
	v_lshlrev_b64 v[164:165], 12, v[164:165]
	v_add_f32_e32 v32, 1.0, v32
	v_rcp_f32_e32 v133, v32
	s_nop 0
	v_lshl_add_u64 v[164:165], v[130:131], 0, v[164:165]
	v_mul_f32_e32 v32, v129, v133
	v_bfe_u32 v133, v32, 16, 1
	v_add3_u32 v32, v32, v133, s1
	global_store_short_d16_hi v[164:165], v32, off
	v_mul_f32_e32 v32, 0xbfb8aa3b, v113
	v_exp_f32_e32 v32, v32
	s_nop 0
	v_add_f32_e32 v32, 1.0, v32
	v_rcp_f32_e32 v133, v32
	s_nop 0
	v_mul_f32_e32 v32, v113, v133
	v_bfe_u32 v133, v32, 16, 1
	v_add3_u32 v32, v32, v133, s1
	global_store_short_d16_hi v[164:165], v32, off offset:128
	v_mul_f32_e32 v32, 0xbfb8aa3b, v82
	v_exp_f32_e32 v32, v32
	s_nop 0
	v_add_f32_e32 v32, 1.0, v32
	v_rcp_f32_e32 v133, v32
	s_nop 0
	v_mul_f32_e32 v32, v82, v133
	v_bfe_u32 v133, v32, 16, 1
	v_add3_u32 v32, v32, v133, s1
	global_store_short_d16_hi v[134:135], v32, off offset:64
	v_mul_f32_e32 v32, 0xbfb8aa3b, v66
	v_exp_f32_e32 v32, v32
	s_nop 0
	v_add_f32_e32 v32, 1.0, v32
	v_rcp_f32_e32 v133, v32
	s_nop 0
	v_mul_f32_e32 v32, v66, v133
	v_bfe_u32 v133, v32, 16, 1
	v_add3_u32 v32, v32, v133, s1
	global_store_short_d16_hi v[134:135], v32, off offset:192
	v_mul_f32_e32 v32, 0xbfb8aa3b, v83
	v_exp_f32_e32 v32, v32
	s_nop 0
	v_add_f32_e32 v32, 1.0, v32
	v_rcp_f32_e32 v133, v32
	s_nop 0
	v_mul_f32_e32 v32, v83, v133
	v_bfe_u32 v133, v32, 16, 1
	v_add3_u32 v32, v32, v133, s1
	global_store_short_d16_hi v[136:137], v32, off offset:64
	v_mul_f32_e32 v32, 0xbfb8aa3b, v67
	v_exp_f32_e32 v32, v32
	s_nop 0
	v_add_f32_e32 v32, 1.0, v32
	v_rcp_f32_e32 v133, v32
	s_nop 0
	v_mul_f32_e32 v32, v67, v133
	v_bfe_u32 v133, v32, 16, 1
	v_add3_u32 v32, v32, v133, s1
	global_store_short_d16_hi v[136:137], v32, off offset:192
	v_mul_f32_e32 v32, 0xbfb8aa3b, v84
	v_exp_f32_e32 v32, v32
	s_nop 0
	v_add_f32_e32 v32, 1.0, v32
	v_rcp_f32_e32 v133, v32
	s_nop 0
	v_mul_f32_e32 v32, v84, v133
	v_bfe_u32 v133, v32, 16, 1
	v_add3_u32 v32, v32, v133, s1
	global_store_short_d16_hi v[138:139], v32, off offset:64
	v_mul_f32_e32 v32, 0xbfb8aa3b, v68
	v_exp_f32_e32 v32, v32
	s_nop 0
	v_add_f32_e32 v32, 1.0, v32
	v_rcp_f32_e32 v133, v32
	s_nop 0
	v_mul_f32_e32 v32, v68, v133
	v_bfe_u32 v133, v32, 16, 1
	v_add3_u32 v32, v32, v133, s1
	global_store_short_d16_hi v[138:139], v32, off offset:192
	v_mul_f32_e32 v32, 0xbfb8aa3b, v85
	v_exp_f32_e32 v32, v32
	s_nop 0
	v_add_f32_e32 v32, 1.0, v32
	v_rcp_f32_e32 v133, v32
	s_nop 0
	v_mul_f32_e32 v32, v85, v133
	v_bfe_u32 v133, v32, 16, 1
	v_add3_u32 v32, v32, v133, s1
	global_store_short_d16_hi v[140:141], v32, off offset:64
	v_mul_f32_e32 v32, 0xbfb8aa3b, v69
	v_exp_f32_e32 v32, v32
	s_nop 0
	v_add_f32_e32 v32, 1.0, v32
	v_rcp_f32_e32 v133, v32
	s_nop 0
	v_mul_f32_e32 v32, v69, v133
	v_bfe_u32 v133, v32, 16, 1
	v_add3_u32 v32, v32, v133, s1
	global_store_short_d16_hi v[140:141], v32, off offset:192
	v_mul_f32_e32 v32, 0xbfb8aa3b, v86
	v_exp_f32_e32 v32, v32
	s_nop 0
	v_add_f32_e32 v32, 1.0, v32
	v_rcp_f32_e32 v133, v32
	s_nop 0
	v_mul_f32_e32 v32, v86, v133
	v_bfe_u32 v133, v32, 16, 1
	v_add3_u32 v32, v32, v133, s1
	global_store_short_d16_hi v[142:143], v32, off offset:64
	v_mul_f32_e32 v32, 0xbfb8aa3b, v70
	v_exp_f32_e32 v32, v32
	s_nop 0
	v_add_f32_e32 v32, 1.0, v32
	v_rcp_f32_e32 v133, v32
	s_nop 0
	v_mul_f32_e32 v32, v70, v133
	v_bfe_u32 v133, v32, 16, 1
	v_add3_u32 v32, v32, v133, s1
	global_store_short_d16_hi v[142:143], v32, off offset:192
	v_mul_f32_e32 v32, 0xbfb8aa3b, v87
	v_exp_f32_e32 v32, v32
	s_nop 0
	v_add_f32_e32 v32, 1.0, v32
	v_rcp_f32_e32 v133, v32
	s_nop 0
	v_mul_f32_e32 v32, v87, v133
	v_bfe_u32 v133, v32, 16, 1
	v_add3_u32 v32, v32, v133, s1
	global_store_short_d16_hi v[144:145], v32, off offset:64
	v_mul_f32_e32 v32, 0xbfb8aa3b, v71
	v_exp_f32_e32 v32, v32
	s_nop 0
	v_add_f32_e32 v32, 1.0, v32
	v_rcp_f32_e32 v133, v32
	s_nop 0
	v_mul_f32_e32 v32, v71, v133
	v_bfe_u32 v133, v32, 16, 1
	v_add3_u32 v32, v32, v133, s1
	global_store_short_d16_hi v[144:145], v32, off offset:192
	v_mul_f32_e32 v32, 0xbfb8aa3b, v88
	v_exp_f32_e32 v32, v32
	s_nop 0
	v_add_f32_e32 v32, 1.0, v32
	v_rcp_f32_e32 v133, v32
	s_nop 0
	v_mul_f32_e32 v32, v88, v133
	v_bfe_u32 v133, v32, 16, 1
	v_add3_u32 v32, v32, v133, s1
	global_store_short_d16_hi v[146:147], v32, off offset:64
	v_mul_f32_e32 v32, 0xbfb8aa3b, v72
	v_exp_f32_e32 v32, v32
	s_nop 0
	v_add_f32_e32 v32, 1.0, v32
	v_rcp_f32_e32 v133, v32
	s_nop 0
	v_mul_f32_e32 v32, v72, v133
	v_bfe_u32 v133, v32, 16, 1
	v_add3_u32 v32, v32, v133, s1
	global_store_short_d16_hi v[146:147], v32, off offset:192
	v_mul_f32_e32 v32, 0xbfb8aa3b, v89
	v_exp_f32_e32 v32, v32
	s_nop 0
	v_add_f32_e32 v32, 1.0, v32
	v_rcp_f32_e32 v133, v32
	s_nop 0
	v_mul_f32_e32 v32, v89, v133
	v_bfe_u32 v133, v32, 16, 1
	v_add3_u32 v32, v32, v133, s1
	global_store_short_d16_hi v[148:149], v32, off offset:64
	v_mul_f32_e32 v32, 0xbfb8aa3b, v73
	v_exp_f32_e32 v32, v32
	s_nop 0
	v_add_f32_e32 v32, 1.0, v32
	v_rcp_f32_e32 v133, v32
	s_nop 0
	v_mul_f32_e32 v32, v73, v133
	v_bfe_u32 v133, v32, 16, 1
	v_add3_u32 v32, v32, v133, s1
	global_store_short_d16_hi v[148:149], v32, off offset:192
	v_mul_f32_e32 v32, 0xbfb8aa3b, v90
	v_exp_f32_e32 v32, v32
	s_nop 0
	v_add_f32_e32 v32, 1.0, v32
	v_rcp_f32_e32 v133, v32
	s_nop 0
	v_mul_f32_e32 v32, v90, v133
	v_bfe_u32 v133, v32, 16, 1
	v_add3_u32 v32, v32, v133, s1
	global_store_short_d16_hi v[150:151], v32, off offset:64
	v_mul_f32_e32 v32, 0xbfb8aa3b, v74
	v_exp_f32_e32 v32, v32
	s_nop 0
	v_add_f32_e32 v32, 1.0, v32
	v_rcp_f32_e32 v133, v32
	s_nop 0
	v_mul_f32_e32 v32, v74, v133
	v_bfe_u32 v133, v32, 16, 1
	v_add3_u32 v32, v32, v133, s1
	global_store_short_d16_hi v[150:151], v32, off offset:192
	v_mul_f32_e32 v32, 0xbfb8aa3b, v91
	v_exp_f32_e32 v32, v32
	s_nop 0
	v_add_f32_e32 v32, 1.0, v32
	v_rcp_f32_e32 v133, v32
	s_nop 0
	v_mul_f32_e32 v32, v91, v133
	v_bfe_u32 v133, v32, 16, 1
	v_add3_u32 v32, v32, v133, s1
	global_store_short_d16_hi v[152:153], v32, off offset:64
	v_mul_f32_e32 v32, 0xbfb8aa3b, v75
	v_exp_f32_e32 v32, v32
	s_nop 0
	v_add_f32_e32 v32, 1.0, v32
	v_rcp_f32_e32 v133, v32
	s_nop 0
	v_mul_f32_e32 v32, v75, v133
	v_bfe_u32 v133, v32, 16, 1
	v_add3_u32 v32, v32, v133, s1
	global_store_short_d16_hi v[152:153], v32, off offset:192
	v_mul_f32_e32 v32, 0xbfb8aa3b, v92
	v_exp_f32_e32 v32, v32
	s_nop 0
	v_add_f32_e32 v32, 1.0, v32
	v_rcp_f32_e32 v133, v32
	s_nop 0
	v_mul_f32_e32 v32, v92, v133
	v_bfe_u32 v133, v32, 16, 1
	v_add3_u32 v32, v32, v133, s1
	global_store_short_d16_hi v[154:155], v32, off offset:64
	v_mul_f32_e32 v32, 0xbfb8aa3b, v76
	v_exp_f32_e32 v32, v32
	s_nop 0
	v_add_f32_e32 v32, 1.0, v32
	v_rcp_f32_e32 v133, v32
	s_nop 0
	v_mul_f32_e32 v32, v76, v133
	v_bfe_u32 v133, v32, 16, 1
	v_add3_u32 v32, v32, v133, s1
	global_store_short_d16_hi v[154:155], v32, off offset:192
	v_mul_f32_e32 v32, 0xbfb8aa3b, v93
	v_exp_f32_e32 v32, v32
	s_nop 0
	v_add_f32_e32 v32, 1.0, v32
	v_rcp_f32_e32 v133, v32
	s_nop 0
	v_mul_f32_e32 v32, v93, v133
	v_bfe_u32 v133, v32, 16, 1
	v_add3_u32 v32, v32, v133, s1
	global_store_short_d16_hi v[156:157], v32, off offset:64
	v_mul_f32_e32 v32, 0xbfb8aa3b, v77
	v_exp_f32_e32 v32, v32
	s_nop 0
	v_add_f32_e32 v32, 1.0, v32
	v_rcp_f32_e32 v133, v32
	s_nop 0
	v_mul_f32_e32 v32, v77, v133
	v_bfe_u32 v133, v32, 16, 1
	v_add3_u32 v32, v32, v133, s1
	global_store_short_d16_hi v[156:157], v32, off offset:192
	v_mul_f32_e32 v32, 0xbfb8aa3b, v94
	v_exp_f32_e32 v32, v32
	s_nop 0
	v_add_f32_e32 v32, 1.0, v32
	v_rcp_f32_e32 v133, v32
	s_nop 0
	v_mul_f32_e32 v32, v94, v133
	v_bfe_u32 v133, v32, 16, 1
	v_add3_u32 v32, v32, v133, s1
	global_store_short_d16_hi v[158:159], v32, off offset:64
	v_mul_f32_e32 v32, 0xbfb8aa3b, v78
	v_exp_f32_e32 v32, v32
	s_nop 0
	v_add_f32_e32 v32, 1.0, v32
	v_rcp_f32_e32 v133, v32
	s_nop 0
	v_mul_f32_e32 v32, v78, v133
	v_bfe_u32 v133, v32, 16, 1
	v_add3_u32 v32, v32, v133, s1
	global_store_short_d16_hi v[158:159], v32, off offset:192
	v_mul_f32_e32 v32, 0xbfb8aa3b, v95
	v_exp_f32_e32 v32, v32
	s_nop 0
	v_add_f32_e32 v32, 1.0, v32
	v_rcp_f32_e32 v133, v32
	s_nop 0
	v_mul_f32_e32 v32, v95, v133
	v_bfe_u32 v133, v32, 16, 1
	v_add3_u32 v32, v32, v133, s1
	global_store_short_d16_hi v[160:161], v32, off offset:64
	v_mul_f32_e32 v32, 0xbfb8aa3b, v79
	v_exp_f32_e32 v32, v32
	s_nop 0
	v_add_f32_e32 v32, 1.0, v32
	v_rcp_f32_e32 v133, v32
	s_nop 0
	v_mul_f32_e32 v32, v79, v133
	v_bfe_u32 v133, v32, 16, 1
	v_add3_u32 v32, v32, v133, s1
	global_store_short_d16_hi v[160:161], v32, off offset:192
	v_mul_f32_e32 v32, 0xbfb8aa3b, v96
	v_exp_f32_e32 v32, v32
	s_nop 0
	v_add_f32_e32 v32, 1.0, v32
	v_rcp_f32_e32 v133, v32
	s_nop 0
	v_mul_f32_e32 v32, v96, v133
	v_bfe_u32 v133, v32, 16, 1
	v_add3_u32 v32, v32, v133, s1
	global_store_short_d16_hi v[162:163], v32, off offset:64
	v_mul_f32_e32 v32, 0xbfb8aa3b, v80
	v_exp_f32_e32 v32, v32
	s_nop 0
	v_add_f32_e32 v32, 1.0, v32
	v_rcp_f32_e32 v133, v32
	s_nop 0
	v_mul_f32_e32 v32, v80, v133
	v_bfe_u32 v133, v32, 16, 1
	v_add3_u32 v32, v32, v133, s1
	global_store_short_d16_hi v[162:163], v32, off offset:192
	v_mul_f32_e32 v32, 0xbfb8aa3b, v97
	v_exp_f32_e32 v32, v32
	s_nop 0
	v_add_f32_e32 v32, 1.0, v32
	v_rcp_f32_e32 v133, v32
	s_nop 0
	v_mul_f32_e32 v32, v97, v133
	v_bfe_u32 v133, v32, 16, 1
	v_add3_u32 v32, v32, v133, s1
	global_store_short_d16_hi v[164:165], v32, off offset:64
	v_mul_f32_e32 v32, 0xbfb8aa3b, v81
	v_exp_f32_e32 v32, v32
	s_nop 0
	v_add_f32_e32 v32, 1.0, v32
	v_rcp_f32_e32 v133, v32
	s_nop 0
	v_mul_f32_e32 v32, v81, v133
	v_bfe_u32 v133, v32, 16, 1
	v_add3_u32 v32, v32, v133, s1
	global_store_short_d16_hi v[164:165], v32, off offset:192
	v_mul_f32_e32 v32, 0xbfb8aa3b, v50
	v_exp_f32_e32 v32, v32
	v_or_b32_e32 v134, 32, v132
	v_ashrrev_i32_e32 v135, 31, v134
	v_lshlrev_b64 v[134:135], 12, v[134:135]
	v_add_f32_e32 v32, 1.0, v32
	v_rcp_f32_e32 v133, v32
	s_nop 0
	v_lshl_add_u64 v[134:135], v[130:131], 0, v[134:135]
	v_mul_f32_e32 v32, v50, v133
	v_bfe_u32 v133, v32, 16, 1
	v_add3_u32 v32, v32, v133, s1
	global_store_short_d16_hi v[134:135], v32, off
	v_mul_f32_e32 v32, 0xbfb8aa3b, v34
	v_exp_f32_e32 v32, v32
	s_nop 0
	v_add_f32_e32 v32, 1.0, v32
	v_rcp_f32_e32 v133, v32
	s_nop 0
	v_mul_f32_e32 v32, v34, v133
	v_bfe_u32 v133, v32, 16, 1
	v_add3_u32 v32, v32, v133, s1
	global_store_short_d16_hi v[134:135], v32, off offset:128
	v_mul_f32_e32 v32, 0xbfb8aa3b, v51
	v_exp_f32_e32 v32, v32
	v_or_b32_e32 v136, 33, v132
	v_ashrrev_i32_e32 v137, 31, v136
	v_lshlrev_b64 v[136:137], 12, v[136:137]
	v_add_f32_e32 v32, 1.0, v32
	v_rcp_f32_e32 v133, v32
	s_nop 0
	v_lshl_add_u64 v[136:137], v[130:131], 0, v[136:137]
	v_mul_f32_e32 v32, v51, v133
	v_bfe_u32 v133, v32, 16, 1
	v_add3_u32 v32, v32, v133, s1
	global_store_short_d16_hi v[136:137], v32, off
	v_mul_f32_e32 v32, 0xbfb8aa3b, v35
	v_exp_f32_e32 v32, v32
	s_nop 0
	v_add_f32_e32 v32, 1.0, v32
	v_rcp_f32_e32 v133, v32
	s_nop 0
	v_mul_f32_e32 v32, v35, v133
	v_bfe_u32 v133, v32, 16, 1
	v_add3_u32 v32, v32, v133, s1
	global_store_short_d16_hi v[136:137], v32, off offset:128
	v_mul_f32_e32 v32, 0xbfb8aa3b, v52
	v_exp_f32_e32 v32, v32
	v_or_b32_e32 v138, 34, v132
	v_ashrrev_i32_e32 v139, 31, v138
	v_lshlrev_b64 v[138:139], 12, v[138:139]
	v_add_f32_e32 v32, 1.0, v32
	v_rcp_f32_e32 v133, v32
	s_nop 0
	v_lshl_add_u64 v[138:139], v[130:131], 0, v[138:139]
	v_mul_f32_e32 v32, v52, v133
	v_bfe_u32 v133, v32, 16, 1
	v_add3_u32 v32, v32, v133, s1
	global_store_short_d16_hi v[138:139], v32, off
	v_mul_f32_e32 v32, 0xbfb8aa3b, v36
	v_exp_f32_e32 v32, v32
	s_nop 0
	v_add_f32_e32 v32, 1.0, v32
	v_rcp_f32_e32 v133, v32
	s_nop 0
	v_mul_f32_e32 v32, v36, v133
	v_bfe_u32 v133, v32, 16, 1
	v_add3_u32 v32, v32, v133, s1
	global_store_short_d16_hi v[138:139], v32, off offset:128
	v_mul_f32_e32 v32, 0xbfb8aa3b, v53
	v_exp_f32_e32 v32, v32
	v_or_b32_e32 v140, 35, v132
	v_ashrrev_i32_e32 v141, 31, v140
	v_lshlrev_b64 v[140:141], 12, v[140:141]
	v_add_f32_e32 v32, 1.0, v32
	v_rcp_f32_e32 v133, v32
	s_nop 0
	v_lshl_add_u64 v[140:141], v[130:131], 0, v[140:141]
	v_mul_f32_e32 v32, v53, v133
	v_bfe_u32 v133, v32, 16, 1
	v_add3_u32 v32, v32, v133, s1
	global_store_short_d16_hi v[140:141], v32, off
	v_mul_f32_e32 v32, 0xbfb8aa3b, v37
	v_exp_f32_e32 v32, v32
	s_nop 0
	v_add_f32_e32 v32, 1.0, v32
	v_rcp_f32_e32 v133, v32
	s_nop 0
	v_mul_f32_e32 v32, v37, v133
	v_bfe_u32 v133, v32, 16, 1
	v_add3_u32 v32, v32, v133, s1
	global_store_short_d16_hi v[140:141], v32, off offset:128
	v_mul_f32_e32 v32, 0xbfb8aa3b, v54
	v_exp_f32_e32 v32, v32
	v_or_b32_e32 v142, 40, v132
	v_ashrrev_i32_e32 v143, 31, v142
	v_lshlrev_b64 v[142:143], 12, v[142:143]
	v_add_f32_e32 v32, 1.0, v32
	v_rcp_f32_e32 v133, v32
	s_nop 0
	v_lshl_add_u64 v[142:143], v[130:131], 0, v[142:143]
	v_mul_f32_e32 v32, v54, v133
	v_bfe_u32 v133, v32, 16, 1
	v_add3_u32 v32, v32, v133, s1
	global_store_short_d16_hi v[142:143], v32, off
	v_mul_f32_e32 v32, 0xbfb8aa3b, v38
	v_exp_f32_e32 v32, v32
	s_nop 0
	v_add_f32_e32 v32, 1.0, v32
	v_rcp_f32_e32 v133, v32
	s_nop 0
	v_mul_f32_e32 v32, v38, v133
	v_bfe_u32 v133, v32, 16, 1
	v_add3_u32 v32, v32, v133, s1
	global_store_short_d16_hi v[142:143], v32, off offset:128
	v_mul_f32_e32 v32, 0xbfb8aa3b, v55
	v_exp_f32_e32 v32, v32
	v_or_b32_e32 v144, 41, v132
	v_ashrrev_i32_e32 v145, 31, v144
	v_lshlrev_b64 v[144:145], 12, v[144:145]
	v_add_f32_e32 v32, 1.0, v32
	v_rcp_f32_e32 v133, v32
	s_nop 0
	v_lshl_add_u64 v[144:145], v[130:131], 0, v[144:145]
	v_mul_f32_e32 v32, v55, v133
	v_bfe_u32 v133, v32, 16, 1
	v_add3_u32 v32, v32, v133, s1
	global_store_short_d16_hi v[144:145], v32, off
	v_mul_f32_e32 v32, 0xbfb8aa3b, v39
	v_exp_f32_e32 v32, v32
	s_nop 0
	v_add_f32_e32 v32, 1.0, v32
	v_rcp_f32_e32 v133, v32
	s_nop 0
	v_mul_f32_e32 v32, v39, v133
	v_bfe_u32 v133, v32, 16, 1
	v_add3_u32 v32, v32, v133, s1
	global_store_short_d16_hi v[144:145], v32, off offset:128
	v_mul_f32_e32 v32, 0xbfb8aa3b, v56
	v_exp_f32_e32 v32, v32
	v_or_b32_e32 v146, 42, v132
	v_ashrrev_i32_e32 v147, 31, v146
	v_lshlrev_b64 v[146:147], 12, v[146:147]
	v_add_f32_e32 v32, 1.0, v32
	v_rcp_f32_e32 v133, v32
	s_nop 0
	v_lshl_add_u64 v[146:147], v[130:131], 0, v[146:147]
	v_mul_f32_e32 v32, v56, v133
	v_bfe_u32 v133, v32, 16, 1
	v_add3_u32 v32, v32, v133, s1
	global_store_short_d16_hi v[146:147], v32, off
	v_mul_f32_e32 v32, 0xbfb8aa3b, v40
	v_exp_f32_e32 v32, v32
	s_nop 0
	v_add_f32_e32 v32, 1.0, v32
	v_rcp_f32_e32 v133, v32
	s_nop 0
	v_mul_f32_e32 v32, v40, v133
	v_bfe_u32 v133, v32, 16, 1
	v_add3_u32 v32, v32, v133, s1
	global_store_short_d16_hi v[146:147], v32, off offset:128
	v_mul_f32_e32 v32, 0xbfb8aa3b, v57
	v_exp_f32_e32 v32, v32
	v_or_b32_e32 v148, 43, v132
	v_ashrrev_i32_e32 v149, 31, v148
	v_lshlrev_b64 v[148:149], 12, v[148:149]
	v_add_f32_e32 v32, 1.0, v32
	v_rcp_f32_e32 v133, v32
	s_nop 0
	v_lshl_add_u64 v[148:149], v[130:131], 0, v[148:149]
	v_mul_f32_e32 v32, v57, v133
	v_bfe_u32 v133, v32, 16, 1
	v_add3_u32 v32, v32, v133, s1
	global_store_short_d16_hi v[148:149], v32, off
	v_mul_f32_e32 v32, 0xbfb8aa3b, v41
	v_exp_f32_e32 v32, v32
	s_nop 0
	v_add_f32_e32 v32, 1.0, v32
	v_rcp_f32_e32 v133, v32
	s_nop 0
	v_mul_f32_e32 v32, v41, v133
	v_bfe_u32 v133, v32, 16, 1
	v_add3_u32 v32, v32, v133, s1
	global_store_short_d16_hi v[148:149], v32, off offset:128
	v_mul_f32_e32 v32, 0xbfb8aa3b, v58
	v_exp_f32_e32 v32, v32
	v_or_b32_e32 v150, 48, v132
	v_ashrrev_i32_e32 v151, 31, v150
	v_lshlrev_b64 v[150:151], 12, v[150:151]
	v_add_f32_e32 v32, 1.0, v32
	v_rcp_f32_e32 v133, v32
	s_nop 0
	v_lshl_add_u64 v[150:151], v[130:131], 0, v[150:151]
	v_mul_f32_e32 v32, v58, v133
	v_bfe_u32 v133, v32, 16, 1
	v_add3_u32 v32, v32, v133, s1
	global_store_short_d16_hi v[150:151], v32, off
	v_mul_f32_e32 v32, 0xbfb8aa3b, v42
	v_exp_f32_e32 v32, v32
	s_nop 0
	v_add_f32_e32 v32, 1.0, v32
	v_rcp_f32_e32 v133, v32
	s_nop 0
	v_mul_f32_e32 v32, v42, v133
	v_bfe_u32 v133, v32, 16, 1
	v_add3_u32 v32, v32, v133, s1
	global_store_short_d16_hi v[150:151], v32, off offset:128
	v_mul_f32_e32 v32, 0xbfb8aa3b, v59
	v_exp_f32_e32 v32, v32
	v_or_b32_e32 v152, 49, v132
	v_ashrrev_i32_e32 v153, 31, v152
	v_lshlrev_b64 v[152:153], 12, v[152:153]
	v_add_f32_e32 v32, 1.0, v32
	v_rcp_f32_e32 v133, v32
	s_nop 0
	v_lshl_add_u64 v[152:153], v[130:131], 0, v[152:153]
	v_mul_f32_e32 v32, v59, v133
	v_bfe_u32 v133, v32, 16, 1
	v_add3_u32 v32, v32, v133, s1
	global_store_short_d16_hi v[152:153], v32, off
	v_mul_f32_e32 v32, 0xbfb8aa3b, v43
	v_exp_f32_e32 v32, v32
	s_nop 0
	v_add_f32_e32 v32, 1.0, v32
	v_rcp_f32_e32 v133, v32
	s_nop 0
	v_mul_f32_e32 v32, v43, v133
	v_bfe_u32 v133, v32, 16, 1
	v_add3_u32 v32, v32, v133, s1
	global_store_short_d16_hi v[152:153], v32, off offset:128
	v_mul_f32_e32 v32, 0xbfb8aa3b, v60
	v_exp_f32_e32 v32, v32
	v_or_b32_e32 v154, 50, v132
	v_ashrrev_i32_e32 v155, 31, v154
	v_lshlrev_b64 v[154:155], 12, v[154:155]
	v_add_f32_e32 v32, 1.0, v32
	v_rcp_f32_e32 v133, v32
	s_nop 0
	v_lshl_add_u64 v[154:155], v[130:131], 0, v[154:155]
	v_mul_f32_e32 v32, v60, v133
	v_bfe_u32 v133, v32, 16, 1
	v_add3_u32 v32, v32, v133, s1
	global_store_short_d16_hi v[154:155], v32, off
	v_mul_f32_e32 v32, 0xbfb8aa3b, v44
	v_exp_f32_e32 v32, v32
	s_nop 0
	v_add_f32_e32 v32, 1.0, v32
	v_rcp_f32_e32 v133, v32
	s_nop 0
	v_mul_f32_e32 v32, v44, v133
	v_bfe_u32 v133, v32, 16, 1
	v_add3_u32 v32, v32, v133, s1
	global_store_short_d16_hi v[154:155], v32, off offset:128
	v_mul_f32_e32 v32, 0xbfb8aa3b, v61
	v_exp_f32_e32 v32, v32
	v_or_b32_e32 v156, 51, v132
	v_ashrrev_i32_e32 v157, 31, v156
	v_lshlrev_b64 v[156:157], 12, v[156:157]
	v_add_f32_e32 v32, 1.0, v32
	v_rcp_f32_e32 v133, v32
	s_nop 0
	v_lshl_add_u64 v[156:157], v[130:131], 0, v[156:157]
	v_mul_f32_e32 v32, v61, v133
	v_bfe_u32 v133, v32, 16, 1
	v_add3_u32 v32, v32, v133, s1
	global_store_short_d16_hi v[156:157], v32, off
	v_mul_f32_e32 v32, 0xbfb8aa3b, v45
	v_exp_f32_e32 v32, v32
	s_nop 0
	v_add_f32_e32 v32, 1.0, v32
	v_rcp_f32_e32 v133, v32
	s_nop 0
	v_mul_f32_e32 v32, v45, v133
	v_bfe_u32 v133, v32, 16, 1
	v_add3_u32 v32, v32, v133, s1
	global_store_short_d16_hi v[156:157], v32, off offset:128
	v_mul_f32_e32 v32, 0xbfb8aa3b, v62
	v_exp_f32_e32 v32, v32
	v_or_b32_e32 v158, 56, v132
	v_ashrrev_i32_e32 v159, 31, v158
	v_lshlrev_b64 v[158:159], 12, v[158:159]
	v_add_f32_e32 v32, 1.0, v32
	v_rcp_f32_e32 v133, v32
	s_nop 0
	v_lshl_add_u64 v[158:159], v[130:131], 0, v[158:159]
	v_mul_f32_e32 v32, v62, v133
	v_bfe_u32 v133, v32, 16, 1
	v_add3_u32 v32, v32, v133, s1
	global_store_short_d16_hi v[158:159], v32, off
	v_mul_f32_e32 v32, 0xbfb8aa3b, v46
	v_exp_f32_e32 v32, v32
	s_nop 0
	v_add_f32_e32 v32, 1.0, v32
	v_rcp_f32_e32 v133, v32
	s_nop 0
	v_mul_f32_e32 v32, v46, v133
	v_bfe_u32 v133, v32, 16, 1
	v_add3_u32 v32, v32, v133, s1
	global_store_short_d16_hi v[158:159], v32, off offset:128
	v_mul_f32_e32 v32, 0xbfb8aa3b, v63
	v_exp_f32_e32 v32, v32
	v_or_b32_e32 v160, 57, v132
	v_ashrrev_i32_e32 v161, 31, v160
	v_lshlrev_b64 v[160:161], 12, v[160:161]
	v_add_f32_e32 v32, 1.0, v32
	v_rcp_f32_e32 v133, v32
	s_nop 0
	v_lshl_add_u64 v[160:161], v[130:131], 0, v[160:161]
	v_mul_f32_e32 v32, v63, v133
	v_bfe_u32 v133, v32, 16, 1
	v_add3_u32 v32, v32, v133, s1
	global_store_short_d16_hi v[160:161], v32, off
	v_mul_f32_e32 v32, 0xbfb8aa3b, v47
	v_exp_f32_e32 v32, v32
	s_nop 0
	v_add_f32_e32 v32, 1.0, v32
	v_rcp_f32_e32 v133, v32
	s_nop 0
	v_mul_f32_e32 v32, v47, v133
	v_bfe_u32 v133, v32, 16, 1
	v_add3_u32 v32, v32, v133, s1
	global_store_short_d16_hi v[160:161], v32, off offset:128
	v_mul_f32_e32 v32, 0xbfb8aa3b, v64
	v_exp_f32_e32 v32, v32
	v_or_b32_e32 v162, 58, v132
	v_ashrrev_i32_e32 v163, 31, v162
	v_lshlrev_b64 v[162:163], 12, v[162:163]
	v_add_f32_e32 v32, 1.0, v32
	v_rcp_f32_e32 v133, v32
	s_nop 0
	v_lshl_add_u64 v[162:163], v[130:131], 0, v[162:163]
	v_or_b32_e32 v132, 59, v132
	v_mul_f32_e32 v32, v64, v133
	v_bfe_u32 v133, v32, 16, 1
	v_add3_u32 v32, v32, v133, s1
	global_store_short_d16_hi v[162:163], v32, off
	v_mul_f32_e32 v32, 0xbfb8aa3b, v48
	v_exp_f32_e32 v32, v32
	s_nop 0
	v_add_f32_e32 v32, 1.0, v32
	v_rcp_f32_e32 v133, v32
	s_nop 0
	v_mul_f32_e32 v32, v48, v133
	v_bfe_u32 v133, v32, 16, 1
	v_add3_u32 v32, v32, v133, s1
	global_store_short_d16_hi v[162:163], v32, off offset:128
	v_mul_f32_e32 v32, 0xbfb8aa3b, v65
	v_exp_f32_e32 v32, v32
	v_ashrrev_i32_e32 v133, 31, v132
	v_lshlrev_b64 v[132:133], 12, v[132:133]
	v_lshl_add_u64 v[130:131], v[130:131], 0, v[132:133]
	v_add_f32_e32 v32, 1.0, v32
	v_rcp_f32_e32 v164, v32
	s_nop 0
	v_mul_f32_e32 v32, v65, v164
	v_bfe_u32 v164, v32, 16, 1
	v_add3_u32 v32, v32, v164, s1
	global_store_short_d16_hi v[130:131], v32, off
	v_mul_f32_e32 v32, 0xbfb8aa3b, v49
	v_exp_f32_e32 v32, v32
	s_nop 0
	v_add_f32_e32 v32, 1.0, v32
	v_rcp_f32_e32 v132, v32
	s_nop 0
	v_mul_f32_e32 v32, v49, v132
	v_bfe_u32 v132, v32, 16, 1
	v_add3_u32 v32, v32, v132, s1
	global_store_short_d16_hi v[130:131], v32, off offset:128
	v_mul_f32_e32 v32, 0xbfb8aa3b, v16
	v_exp_f32_e32 v32, v32
	s_nop 0
	v_add_f32_e32 v32, 1.0, v32
	v_rcp_f32_e32 v132, v32
	s_nop 0
	v_mul_f32_e32 v32, v16, v132
	v_bfe_u32 v132, v32, 16, 1
	v_add3_u32 v32, v32, v132, s1
	global_store_short_d16_hi v[134:135], v32, off offset:64
	v_mul_f32_e32 v32, 0xbfb8aa3b, v0
	v_exp_f32_e32 v32, v32
	s_nop 0
	v_add_f32_e32 v32, 1.0, v32
	v_rcp_f32_e32 v132, v32
	s_nop 0
	v_mul_f32_e32 v32, v0, v132
	v_bfe_u32 v132, v32, 16, 1
	v_add3_u32 v32, v32, v132, s1
	global_store_short_d16_hi v[134:135], v32, off offset:192
	v_mul_f32_e32 v32, 0xbfb8aa3b, v17
	v_exp_f32_e32 v32, v32
	s_nop 0
	v_add_f32_e32 v32, 1.0, v32
	v_rcp_f32_e32 v132, v32
	s_nop 0
	v_mul_f32_e32 v32, v17, v132
	v_bfe_u32 v132, v32, 16, 1
	v_add3_u32 v32, v32, v132, s1
	global_store_short_d16_hi v[136:137], v32, off offset:64
	v_mul_f32_e32 v32, 0xbfb8aa3b, v1
	v_exp_f32_e32 v32, v32
	s_nop 0
	v_add_f32_e32 v32, 1.0, v32
	v_rcp_f32_e32 v132, v32
	s_nop 0
	v_mul_f32_e32 v32, v1, v132
	v_bfe_u32 v132, v32, 16, 1
	v_add3_u32 v32, v32, v132, s1
	global_store_short_d16_hi v[136:137], v32, off offset:192
	v_mul_f32_e32 v32, 0xbfb8aa3b, v18
	v_exp_f32_e32 v32, v32
	s_nop 0
	v_add_f32_e32 v32, 1.0, v32
	v_rcp_f32_e32 v132, v32
	s_nop 0
	v_mul_f32_e32 v32, v18, v132
	v_bfe_u32 v132, v32, 16, 1
	v_add3_u32 v32, v32, v132, s1
	global_store_short_d16_hi v[138:139], v32, off offset:64
	v_mul_f32_e32 v32, 0xbfb8aa3b, v2
	v_exp_f32_e32 v32, v32
	s_nop 0
	v_add_f32_e32 v32, 1.0, v32
	v_rcp_f32_e32 v132, v32
	s_nop 0
	v_mul_f32_e32 v32, v2, v132
	v_bfe_u32 v132, v32, 16, 1
	v_add3_u32 v32, v32, v132, s1
	global_store_short_d16_hi v[138:139], v32, off offset:192
	v_mul_f32_e32 v32, 0xbfb8aa3b, v19
	v_exp_f32_e32 v32, v32
	s_nop 0
	v_add_f32_e32 v32, 1.0, v32
	v_rcp_f32_e32 v132, v32
	s_nop 0
	v_mul_f32_e32 v32, v19, v132
	v_bfe_u32 v132, v32, 16, 1
	v_add3_u32 v32, v32, v132, s1
	global_store_short_d16_hi v[140:141], v32, off offset:64
	v_mul_f32_e32 v32, 0xbfb8aa3b, v3
	v_exp_f32_e32 v32, v32
	s_nop 0
	v_add_f32_e32 v32, 1.0, v32
	v_rcp_f32_e32 v132, v32
	s_nop 0
	v_mul_f32_e32 v32, v3, v132
	v_bfe_u32 v132, v32, 16, 1
	v_add3_u32 v32, v32, v132, s1
	global_store_short_d16_hi v[140:141], v32, off offset:192
	v_mul_f32_e32 v32, 0xbfb8aa3b, v20
	v_exp_f32_e32 v32, v32
	s_nop 0
	v_add_f32_e32 v32, 1.0, v32
	v_rcp_f32_e32 v132, v32
	s_nop 0
	v_mul_f32_e32 v32, v20, v132
	v_bfe_u32 v132, v32, 16, 1
	v_add3_u32 v32, v32, v132, s1
	global_store_short_d16_hi v[142:143], v32, off offset:64
	v_mul_f32_e32 v32, 0xbfb8aa3b, v4
	v_exp_f32_e32 v32, v32
	s_nop 0
	v_add_f32_e32 v32, 1.0, v32
	v_rcp_f32_e32 v132, v32
	s_nop 0
	v_mul_f32_e32 v32, v4, v132
	v_bfe_u32 v132, v32, 16, 1
	v_add3_u32 v32, v32, v132, s1
	global_store_short_d16_hi v[142:143], v32, off offset:192
	v_mul_f32_e32 v32, 0xbfb8aa3b, v21
	v_exp_f32_e32 v32, v32
	s_nop 0
	v_add_f32_e32 v32, 1.0, v32
	v_rcp_f32_e32 v132, v32
	s_nop 0
	v_mul_f32_e32 v32, v21, v132
	v_bfe_u32 v132, v32, 16, 1
	v_add3_u32 v32, v32, v132, s1
	global_store_short_d16_hi v[144:145], v32, off offset:64
	v_mul_f32_e32 v32, 0xbfb8aa3b, v5
	v_exp_f32_e32 v32, v32
	s_nop 0
	v_add_f32_e32 v32, 1.0, v32
	v_rcp_f32_e32 v132, v32
	s_nop 0
	v_mul_f32_e32 v32, v5, v132
	v_bfe_u32 v132, v32, 16, 1
	v_add3_u32 v32, v32, v132, s1
	global_store_short_d16_hi v[144:145], v32, off offset:192
	v_mul_f32_e32 v32, 0xbfb8aa3b, v22
	v_exp_f32_e32 v32, v32
	s_nop 0
	v_add_f32_e32 v32, 1.0, v32
	v_rcp_f32_e32 v132, v32
	s_nop 0
	v_mul_f32_e32 v32, v22, v132
	v_bfe_u32 v132, v32, 16, 1
	v_add3_u32 v32, v32, v132, s1
	global_store_short_d16_hi v[146:147], v32, off offset:64
	v_mul_f32_e32 v32, 0xbfb8aa3b, v6
	v_exp_f32_e32 v32, v32
	s_nop 0
	v_add_f32_e32 v32, 1.0, v32
	v_rcp_f32_e32 v132, v32
	s_nop 0
	v_mul_f32_e32 v32, v6, v132
	v_bfe_u32 v132, v32, 16, 1
	v_add3_u32 v32, v32, v132, s1
	global_store_short_d16_hi v[146:147], v32, off offset:192
	v_mul_f32_e32 v32, 0xbfb8aa3b, v23
	v_exp_f32_e32 v32, v32
	s_nop 0
	v_add_f32_e32 v32, 1.0, v32
	v_rcp_f32_e32 v132, v32
	s_nop 0
	v_mul_f32_e32 v32, v23, v132
	v_bfe_u32 v132, v32, 16, 1
	v_add3_u32 v32, v32, v132, s1
	global_store_short_d16_hi v[148:149], v32, off offset:64
	v_mul_f32_e32 v32, 0xbfb8aa3b, v7
	v_exp_f32_e32 v32, v32
	s_nop 0
	v_add_f32_e32 v32, 1.0, v32
	v_rcp_f32_e32 v132, v32
	s_nop 0
	v_mul_f32_e32 v32, v7, v132
	v_bfe_u32 v132, v32, 16, 1
	v_add3_u32 v32, v32, v132, s1
	global_store_short_d16_hi v[148:149], v32, off offset:192
	v_mul_f32_e32 v32, 0xbfb8aa3b, v24
	v_exp_f32_e32 v32, v32
	s_nop 0
	v_add_f32_e32 v32, 1.0, v32
	v_rcp_f32_e32 v132, v32
	s_nop 0
	v_mul_f32_e32 v32, v24, v132
	v_bfe_u32 v132, v32, 16, 1
	v_add3_u32 v32, v32, v132, s1
	global_store_short_d16_hi v[150:151], v32, off offset:64
	v_mul_f32_e32 v32, 0xbfb8aa3b, v8
	v_exp_f32_e32 v32, v32
	s_nop 0
	v_add_f32_e32 v32, 1.0, v32
	v_rcp_f32_e32 v132, v32
	s_nop 0
	v_mul_f32_e32 v32, v8, v132
	v_bfe_u32 v132, v32, 16, 1
	v_add3_u32 v32, v32, v132, s1
	global_store_short_d16_hi v[150:151], v32, off offset:192
	v_mul_f32_e32 v32, 0xbfb8aa3b, v25
	v_exp_f32_e32 v32, v32
	s_nop 0
	v_add_f32_e32 v32, 1.0, v32
	v_rcp_f32_e32 v132, v32
	s_nop 0
	v_mul_f32_e32 v32, v25, v132
	v_bfe_u32 v132, v32, 16, 1
	v_add3_u32 v32, v32, v132, s1
	global_store_short_d16_hi v[152:153], v32, off offset:64
	v_mul_f32_e32 v32, 0xbfb8aa3b, v9
	v_exp_f32_e32 v32, v32
	s_nop 0
	v_add_f32_e32 v32, 1.0, v32
	v_rcp_f32_e32 v132, v32
	s_nop 0
	v_mul_f32_e32 v32, v9, v132
	v_bfe_u32 v132, v32, 16, 1
	v_add3_u32 v32, v32, v132, s1
	global_store_short_d16_hi v[152:153], v32, off offset:192
	v_mul_f32_e32 v32, 0xbfb8aa3b, v26
	v_exp_f32_e32 v32, v32
	s_nop 0
	v_add_f32_e32 v32, 1.0, v32
	v_rcp_f32_e32 v132, v32
	s_nop 0
	v_mul_f32_e32 v32, v26, v132
	v_bfe_u32 v132, v32, 16, 1
	v_add3_u32 v32, v32, v132, s1
	global_store_short_d16_hi v[154:155], v32, off offset:64
	v_mul_f32_e32 v32, 0xbfb8aa3b, v10
	v_exp_f32_e32 v32, v32
	s_nop 0
	v_add_f32_e32 v32, 1.0, v32
	v_rcp_f32_e32 v132, v32
	s_nop 0
	v_mul_f32_e32 v32, v10, v132
	v_bfe_u32 v132, v32, 16, 1
	v_add3_u32 v32, v32, v132, s1
	global_store_short_d16_hi v[154:155], v32, off offset:192
	v_mul_f32_e32 v32, 0xbfb8aa3b, v27
	v_exp_f32_e32 v32, v32
	s_nop 0
	v_add_f32_e32 v32, 1.0, v32
	v_rcp_f32_e32 v132, v32
	s_nop 0
	v_mul_f32_e32 v32, v27, v132
	v_bfe_u32 v132, v32, 16, 1
	v_add3_u32 v32, v32, v132, s1
	global_store_short_d16_hi v[156:157], v32, off offset:64
	v_mul_f32_e32 v32, 0xbfb8aa3b, v11
	v_exp_f32_e32 v32, v32
	s_nop 0
	v_add_f32_e32 v32, 1.0, v32
	v_rcp_f32_e32 v132, v32
	s_nop 0
	v_mul_f32_e32 v32, v11, v132
	v_bfe_u32 v132, v32, 16, 1
	v_add3_u32 v32, v32, v132, s1
	global_store_short_d16_hi v[156:157], v32, off offset:192
	v_mul_f32_e32 v32, 0xbfb8aa3b, v28
	v_exp_f32_e32 v32, v32
	s_nop 0
	v_add_f32_e32 v32, 1.0, v32
	v_rcp_f32_e32 v132, v32
	s_nop 0
	v_mul_f32_e32 v32, v28, v132
	v_bfe_u32 v132, v32, 16, 1
	v_add3_u32 v32, v32, v132, s1
	global_store_short_d16_hi v[158:159], v32, off offset:64
	v_mul_f32_e32 v32, 0xbfb8aa3b, v12
	v_exp_f32_e32 v32, v32
	s_nop 0
	v_add_f32_e32 v32, 1.0, v32
	v_rcp_f32_e32 v132, v32
	s_nop 0
	v_mul_f32_e32 v32, v12, v132
	v_bfe_u32 v132, v32, 16, 1
	v_add3_u32 v32, v32, v132, s1
	global_store_short_d16_hi v[158:159], v32, off offset:192
	v_mul_f32_e32 v32, 0xbfb8aa3b, v29
	v_exp_f32_e32 v32, v32
	s_nop 0
	v_add_f32_e32 v32, 1.0, v32
	v_rcp_f32_e32 v132, v32
	s_nop 0
	v_mul_f32_e32 v32, v29, v132
	v_bfe_u32 v132, v32, 16, 1
	v_add3_u32 v32, v32, v132, s1
	global_store_short_d16_hi v[160:161], v32, off offset:64
	v_mul_f32_e32 v32, 0xbfb8aa3b, v13
	v_exp_f32_e32 v32, v32
	s_nop 0
	v_add_f32_e32 v32, 1.0, v32
	v_rcp_f32_e32 v132, v32
	s_nop 0
	v_mul_f32_e32 v32, v13, v132
	v_bfe_u32 v132, v32, 16, 1
	v_add3_u32 v32, v32, v132, s1
	global_store_short_d16_hi v[160:161], v32, off offset:192
	v_mul_f32_e32 v32, 0xbfb8aa3b, v30
	v_exp_f32_e32 v32, v32
	s_nop 0
	v_add_f32_e32 v32, 1.0, v32
	v_rcp_f32_e32 v132, v32
	s_nop 0
	v_mul_f32_e32 v32, v30, v132
	v_bfe_u32 v132, v32, 16, 1
	v_add3_u32 v32, v32, v132, s1
	global_store_short_d16_hi v[162:163], v32, off offset:64
	v_mul_f32_e32 v32, 0xbfb8aa3b, v14
	v_exp_f32_e32 v32, v32
	s_nop 0
	v_add_f32_e32 v32, 1.0, v32
	v_rcp_f32_e32 v132, v32
	s_nop 0
	v_mul_f32_e32 v32, v14, v132
	v_bfe_u32 v132, v32, 16, 1
	v_add3_u32 v32, v32, v132, s1
	global_store_short_d16_hi v[162:163], v32, off offset:192
	v_mul_f32_e32 v32, 0xbfb8aa3b, v31
	v_exp_f32_e32 v32, v32
	s_nop 0
	v_add_f32_e32 v32, 1.0, v32
	v_rcp_f32_e32 v132, v32
	s_nop 0
	v_mul_f32_e32 v32, v31, v132
	v_bfe_u32 v132, v32, 16, 1
	v_add3_u32 v32, v32, v132, s1
	global_store_short_d16_hi v[130:131], v32, off offset:64
	v_mul_f32_e32 v32, 0xbfb8aa3b, v15
	v_exp_f32_e32 v32, v32
	s_nop 0
	v_add_f32_e32 v32, 1.0, v32
	v_rcp_f32_e32 v132, v32
	s_nop 0
	s_mov_b64 s[2:3], 0
	v_mul_f32_e32 v32, v15, v132
	v_bfe_u32 v132, v32, 16, 1
	v_add3_u32 v32, v32, v132, s1
	global_store_short_d16_hi v[130:131], v32, off offset:192

.LBB0_2158:
	s_lshl_b32 s1, s0, 3
	s_or_b32 s2, s1, s10
	s_ashr_i32 s3, s2, 31
	s_lshl_b64 s[2:3], s[2:3], 18
	s_add_u32 s1, s56, s2
	s_addc_u32 s2, s57, s3
	s_lshl_b32 s3, s8, 16
	s_add_u32 s1, s1, s3
	s_addc_u32 s3, s2, 0
	s_lshl_b32 s2, s9, 1
	s_add_u32 s2, s1, s2
	s_addc_u32 s3, s3, 0
	s_lshl_b32 s0, s0, 8
	s_ashr_i32 s1, s0, 31
	v_readlane_b32 s12, v248, 46
	s_lshl_b64 s[0:1], s[0:1], 2
	v_readlane_b32 s22, v248, 56
	v_readlane_b32 s23, v248, 57
	s_add_u32 s0, s22, s0
	v_mov_b32_e32 v32, v206
	s_addc_u32 s1, s23, s1
	s_lshl_b32 s4, s9, 2
	s_add_u32 s0, s0, s4
	v_lshrrev_b32_e32 v67, 3, v32
	v_ashrrev_i32_e32 v66, 1, v32
	v_and_b32_e32 v67, 4, v67
	s_movk_i32 s4, 0xffc0
	v_and_or_b32 v66, v66, s4, v67
	v_lshrrev_b32_e32 v67, 1, v32
	v_and_b32_e32 v32, 31, v32
	v_and_or_b32 v32, v67, 32, v32
	s_addc_u32 s1, s1, 0
	v_lshlrev_b32_e32 v67, 2, v32
	global_load_dword v71, v67, s[0:1]
	global_load_dword v70, v67, s[0:1] offset:256
	v_lshlrev_b32_e32 v32, 1, v32
	v_lshl_add_u64 v[68:69], s[2:3], 0, v[32:33]
	s_movk_i32 s2, 0x7fff
	v_readlane_b32 s13, v248, 47
	v_readlane_b32 s14, v248, 48
	v_readlane_b32 s15, v248, 49
	v_readlane_b32 s16, v248, 50
	v_readlane_b32 s17, v248, 51
	v_readlane_b32 s18, v248, 52
	v_readlane_b32 s19, v248, 53
	v_readlane_b32 s20, v248, 54
	v_readlane_b32 s21, v248, 55
	v_readlane_b32 s24, v248, 58
	v_readlane_b32 s25, v248, 59
	v_readlane_b32 s26, v248, 60
	v_readlane_b32 s27, v248, 61
	s_waitcnt vmcnt(1)
	v_add_f32_e32 v32, v50, v71
	v_mul_f32_e32 v50, 0x3d372713, v32
	v_mul_f32_e32 v50, v32, v50
	v_fma_f32 v50, v32, v50, v32
	v_mul_f32_e32 v50, 0x3f4c422a, v50
	v_mul_f32_e32 v50, -2.0, v50
	v_mul_f32_e32 v50, 0x3fb8aa3b, v50
	v_exp_f32_e32 v50, v50
	v_add_f32_e32 v16, v16, v71
	s_waitcnt vmcnt(0)
	v_add_f32_e32 v0, v0, v70
	v_add_f32_e32 v2, v2, v70
	v_add_f32_e32 v50, 1.0, v50
	v_rcp_f32_e32 v67, v50
	s_nop 0
	v_mul_f32_e32 v32, v32, v67
	v_ashrrev_i32_e32 v67, 31, v66
	v_bfe_u32 v50, v32, 16, 1
	v_lshlrev_b64 v[72:73], 9, v[66:67]
	v_add3_u32 v32, v32, v50, s2
	v_lshl_add_u64 v[72:73], v[68:69], 0, v[72:73]
	global_store_short_d16_hi v[72:73], v32, off
	v_add_f32_e32 v32, v34, v70
	v_mul_f32_e32 v34, 0x3d372713, v32
	v_mul_f32_e32 v34, v32, v34
	v_fma_f32 v34, v32, v34, v32
	v_mul_f32_e32 v34, 0x3f4c422a, v34
	v_mul_f32_e32 v34, -2.0, v34
	v_mul_f32_e32 v34, 0x3fb8aa3b, v34
	v_exp_f32_e32 v34, v34
	s_nop 0
	v_add_f32_e32 v34, 1.0, v34
	v_rcp_f32_e32 v50, v34
	s_nop 0
	v_mul_f32_e32 v32, v32, v50
	v_bfe_u32 v34, v32, 16, 1
	v_add3_u32 v32, v32, v34, s2
	global_store_short_d16_hi v[72:73], v32, off offset:128
	v_add_f32_e32 v32, v51, v71
	v_mul_f32_e32 v34, 0x3d372713, v32
	v_mul_f32_e32 v34, v32, v34
	v_fma_f32 v34, v32, v34, v32
	v_mul_f32_e32 v34, 0x3f4c422a, v34
	v_mul_f32_e32 v34, -2.0, v34
	v_mul_f32_e32 v34, 0x3fb8aa3b, v34
	v_exp_f32_e32 v34, v34
	s_nop 0
	v_add_f32_e32 v34, 1.0, v34
	v_rcp_f32_e32 v50, v34
	s_nop 0
	v_mul_f32_e32 v32, v32, v50
	v_or_b32_e32 v50, 1, v66
	v_ashrrev_i32_e32 v51, 31, v50
	v_bfe_u32 v34, v32, 16, 1
	v_lshlrev_b64 v[50:51], 9, v[50:51]
	v_add3_u32 v32, v32, v34, s2
	v_lshl_add_u64 v[50:51], v[68:69], 0, v[50:51]
	global_store_short_d16_hi v[50:51], v32, off
	v_add_f32_e32 v32, v35, v70
	v_mul_f32_e32 v34, 0x3d372713, v32
	v_mul_f32_e32 v34, v32, v34
	v_fma_f32 v34, v32, v34, v32
	v_mul_f32_e32 v34, 0x3f4c422a, v34
	v_mul_f32_e32 v34, -2.0, v34
	v_mul_f32_e32 v34, 0x3fb8aa3b, v34
	v_exp_f32_e32 v34, v34
	s_nop 0
	v_add_f32_e32 v34, 1.0, v34
	v_rcp_f32_e32 v35, v34
	s_nop 0
	v_mul_f32_e32 v32, v32, v35
	v_bfe_u32 v34, v32, 16, 1
	v_add3_u32 v32, v32, v34, s2
	global_store_short_d16_hi v[50:51], v32, off offset:128
	v_add_f32_e32 v32, v52, v71
	v_mul_f32_e32 v34, 0x3d372713, v32
	v_mul_f32_e32 v34, v32, v34
	v_fma_f32 v34, v32, v34, v32
	v_mul_f32_e32 v34, 0x3f4c422a, v34
	v_mul_f32_e32 v34, -2.0, v34
	v_mul_f32_e32 v34, 0x3fb8aa3b, v34
	v_exp_f32_e32 v34, v34
	s_nop 0
	v_add_f32_e32 v34, 1.0, v34
	v_rcp_f32_e32 v35, v34
	s_nop 0
	v_mul_f32_e32 v32, v32, v35
	v_bfe_u32 v34, v32, 16, 1
	v_add3_u32 v32, v32, v34, s2
	v_or_b32_e32 v34, 2, v66
	v_ashrrev_i32_e32 v35, 31, v34
	v_lshlrev_b64 v[34:35], 9, v[34:35]
	v_lshl_add_u64 v[34:35], v[68:69], 0, v[34:35]
	global_store_short_d16_hi v[34:35], v32, off
	v_add_f32_e32 v32, v36, v70
	v_mul_f32_e32 v36, 0x3d372713, v32
	v_mul_f32_e32 v36, v32, v36
	v_fma_f32 v36, v32, v36, v32
	v_mul_f32_e32 v36, 0x3f4c422a, v36
	v_mul_f32_e32 v36, -2.0, v36
	v_mul_f32_e32 v36, 0x3fb8aa3b, v36
	v_exp_f32_e32 v36, v36
	s_nop 0
	v_add_f32_e32 v36, 1.0, v36
	v_rcp_f32_e32 v50, v36
	s_nop 0
	v_mul_f32_e32 v32, v32, v50
	v_bfe_u32 v36, v32, 16, 1
	v_add3_u32 v32, v32, v36, s2
	global_store_short_d16_hi v[34:35], v32, off offset:128
	v_add_f32_e32 v32, v53, v71
	v_mul_f32_e32 v34, 0x3d372713, v32
	v_mul_f32_e32 v34, v32, v34
	v_fma_f32 v34, v32, v34, v32
	v_mul_f32_e32 v34, 0x3f4c422a, v34
	v_mul_f32_e32 v34, -2.0, v34
	v_mul_f32_e32 v34, 0x3fb8aa3b, v34
	v_exp_f32_e32 v34, v34
	s_nop 0
	v_add_f32_e32 v34, 1.0, v34
	v_rcp_f32_e32 v35, v34
	s_nop 0
	v_mul_f32_e32 v32, v32, v35
	v_bfe_u32 v34, v32, 16, 1
	v_add3_u32 v32, v32, v34, s2
	v_or_b32_e32 v34, 3, v66
	v_ashrrev_i32_e32 v35, 31, v34
	v_lshlrev_b64 v[34:35], 9, v[34:35]
	v_lshl_add_u64 v[34:35], v[68:69], 0, v[34:35]
	global_store_short_d16_hi v[34:35], v32, off
	v_add_f32_e32 v32, v37, v70
	v_mul_f32_e32 v36, 0x3d372713, v32
	v_mul_f32_e32 v36, v32, v36
	v_fma_f32 v36, v32, v36, v32
	v_mul_f32_e32 v36, 0x3f4c422a, v36
	v_mul_f32_e32 v36, -2.0, v36
	v_mul_f32_e32 v36, 0x3fb8aa3b, v36
	v_exp_f32_e32 v36, v36
	s_nop 0
	v_add_f32_e32 v36, 1.0, v36
	v_rcp_f32_e32 v37, v36
	s_nop 0
	v_mul_f32_e32 v32, v32, v37
	v_bfe_u32 v36, v32, 16, 1
	v_add3_u32 v32, v32, v36, s2
	global_store_short_d16_hi v[34:35], v32, off offset:128
	v_add_f32_e32 v32, v54, v71
	v_mul_f32_e32 v35, 0x3d372713, v32
	v_mul_f32_e32 v35, v32, v35
	v_fma_f32 v35, v32, v35, v32
	v_mul_f32_e32 v35, 0x3f4c422a, v35
	v_mul_f32_e32 v35, -2.0, v35
	v_mul_f32_e32 v35, 0x3fb8aa3b, v35
	v_exp_f32_e32 v35, v35
	v_or_b32_e32 v34, 8, v66
	v_add_f32_e32 v35, 1.0, v35
	v_rcp_f32_e32 v36, v35
	s_nop 0
	v_mul_f32_e32 v32, v32, v36
	v_bfe_u32 v35, v32, 16, 1
	v_add3_u32 v32, v32, v35, s2
	v_ashrrev_i32_e32 v35, 31, v34
	v_lshlrev_b64 v[34:35], 9, v[34:35]
	v_lshl_add_u64 v[34:35], v[68:69], 0, v[34:35]
	global_store_short_d16_hi v[34:35], v32, off
	v_add_f32_e32 v32, v38, v70
	v_mul_f32_e32 v36, 0x3d372713, v32
	v_mul_f32_e32 v36, v32, v36
	v_fma_f32 v36, v32, v36, v32
	v_mul_f32_e32 v36, 0x3f4c422a, v36
	v_mul_f32_e32 v36, -2.0, v36
	v_mul_f32_e32 v36, 0x3fb8aa3b, v36
	v_exp_f32_e32 v36, v36
	s_nop 0
	v_add_f32_e32 v36, 1.0, v36
	v_rcp_f32_e32 v37, v36
	s_nop 0
	v_mul_f32_e32 v32, v32, v37
	v_bfe_u32 v36, v32, 16, 1
	v_add3_u32 v32, v32, v36, s2
	global_store_short_d16_hi v[34:35], v32, off offset:128
	v_add_f32_e32 v32, v55, v71
	v_mul_f32_e32 v34, 0x3d372713, v32
	v_mul_f32_e32 v34, v32, v34
	v_fma_f32 v34, v32, v34, v32
	v_mul_f32_e32 v34, 0x3f4c422a, v34
	v_mul_f32_e32 v34, -2.0, v34
	v_mul_f32_e32 v34, 0x3fb8aa3b, v34
	v_exp_f32_e32 v34, v34
	s_nop 0
	v_add_f32_e32 v34, 1.0, v34
	v_rcp_f32_e32 v35, v34
	s_nop 0
	v_mul_f32_e32 v32, v32, v35
	v_bfe_u32 v34, v32, 16, 1
	v_add3_u32 v32, v32, v34, s2
	v_or_b32_e32 v34, 9, v66
	v_ashrrev_i32_e32 v35, 31, v34
	v_lshlrev_b64 v[34:35], 9, v[34:35]
	v_lshl_add_u64 v[34:35], v[68:69], 0, v[34:35]
	global_store_short_d16_hi v[34:35], v32, off
	v_add_f32_e32 v32, v39, v70
	v_mul_f32_e32 v36, 0x3d372713, v32
	v_mul_f32_e32 v36, v32, v36
	v_fma_f32 v36, v32, v36, v32
	v_mul_f32_e32 v36, 0x3f4c422a, v36
	v_mul_f32_e32 v36, -2.0, v36
	v_mul_f32_e32 v36, 0x3fb8aa3b, v36
	v_exp_f32_e32 v36, v36
	s_nop 0
	v_add_f32_e32 v36, 1.0, v36
	v_rcp_f32_e32 v37, v36
	s_nop 0
	v_mul_f32_e32 v32, v32, v37
	v_bfe_u32 v36, v32, 16, 1
	v_add3_u32 v32, v32, v36, s2
	global_store_short_d16_hi v[34:35], v32, off offset:128
	v_add_f32_e32 v32, v56, v71
	v_mul_f32_e32 v34, 0x3d372713, v32
	v_mul_f32_e32 v34, v32, v34
	v_fma_f32 v34, v32, v34, v32
	v_mul_f32_e32 v34, 0x3f4c422a, v34
	v_mul_f32_e32 v34, -2.0, v34
	v_mul_f32_e32 v34, 0x3fb8aa3b, v34
	v_exp_f32_e32 v34, v34
	s_nop 0
	v_add_f32_e32 v34, 1.0, v34
	v_rcp_f32_e32 v35, v34
	s_nop 0
	v_mul_f32_e32 v32, v32, v35
	v_bfe_u32 v34, v32, 16, 1
	v_add3_u32 v32, v32, v34, s2
	v_or_b32_e32 v34, 10, v66
	v_ashrrev_i32_e32 v35, 31, v34
	v_lshlrev_b64 v[34:35], 9, v[34:35]
	v_lshl_add_u64 v[34:35], v[68:69], 0, v[34:35]
	global_store_short_d16_hi v[34:35], v32, off
	v_add_f32_e32 v32, v40, v70
	v_mul_f32_e32 v36, 0x3d372713, v32
	v_mul_f32_e32 v36, v32, v36
	v_fma_f32 v36, v32, v36, v32
	v_mul_f32_e32 v36, 0x3f4c422a, v36
	v_mul_f32_e32 v36, -2.0, v36
	v_mul_f32_e32 v36, 0x3fb8aa3b, v36
	v_exp_f32_e32 v36, v36
	s_nop 0
	v_add_f32_e32 v36, 1.0, v36
	v_rcp_f32_e32 v37, v36
	s_nop 0
	v_mul_f32_e32 v32, v32, v37
	v_bfe_u32 v36, v32, 16, 1
	v_add3_u32 v32, v32, v36, s2
	global_store_short_d16_hi v[34:35], v32, off offset:128
	v_add_f32_e32 v32, v57, v71
	v_mul_f32_e32 v34, 0x3d372713, v32
	v_mul_f32_e32 v34, v32, v34
	v_fma_f32 v34, v32, v34, v32
	v_mul_f32_e32 v34, 0x3f4c422a, v34
	v_mul_f32_e32 v34, -2.0, v34
	v_mul_f32_e32 v34, 0x3fb8aa3b, v34
	v_exp_f32_e32 v34, v34
	s_nop 0
	v_add_f32_e32 v34, 1.0, v34
	v_rcp_f32_e32 v35, v34
	s_nop 0
	v_mul_f32_e32 v32, v32, v35
	v_bfe_u32 v34, v32, 16, 1
	v_add3_u32 v32, v32, v34, s2
	v_or_b32_e32 v34, 11, v66
	v_ashrrev_i32_e32 v35, 31, v34
	v_lshlrev_b64 v[34:35], 9, v[34:35]
	v_lshl_add_u64 v[34:35], v[68:69], 0, v[34:35]
	global_store_short_d16_hi v[34:35], v32, off
	v_add_f32_e32 v32, v41, v70
	v_mul_f32_e32 v36, 0x3d372713, v32
	v_mul_f32_e32 v36, v32, v36
	v_fma_f32 v36, v32, v36, v32
	v_mul_f32_e32 v36, 0x3f4c422a, v36
	v_mul_f32_e32 v36, -2.0, v36
	v_mul_f32_e32 v36, 0x3fb8aa3b, v36
	v_exp_f32_e32 v36, v36
	s_nop 0
	v_add_f32_e32 v36, 1.0, v36
	v_rcp_f32_e32 v37, v36
	s_nop 0
	v_mul_f32_e32 v32, v32, v37
	v_bfe_u32 v36, v32, 16, 1
	v_add3_u32 v32, v32, v36, s2
	global_store_short_d16_hi v[34:35], v32, off offset:128
	v_add_f32_e32 v32, v58, v71
	v_mul_f32_e32 v35, 0x3d372713, v32
	v_mul_f32_e32 v35, v32, v35
	v_fma_f32 v35, v32, v35, v32
	v_mul_f32_e32 v35, 0x3f4c422a, v35
	v_mul_f32_e32 v35, -2.0, v35
	v_mul_f32_e32 v35, 0x3fb8aa3b, v35
	v_exp_f32_e32 v35, v35
	v_or_b32_e32 v34, 16, v66
	v_add_f32_e32 v35, 1.0, v35
	v_rcp_f32_e32 v36, v35
	s_nop 0
	v_mul_f32_e32 v32, v32, v36
	v_bfe_u32 v35, v32, 16, 1
	v_add3_u32 v32, v32, v35, s2
	v_ashrrev_i32_e32 v35, 31, v34
	v_lshlrev_b64 v[34:35], 9, v[34:35]
	v_lshl_add_u64 v[34:35], v[68:69], 0, v[34:35]
	global_store_short_d16_hi v[34:35], v32, off
	v_add_f32_e32 v32, v42, v70
	v_mul_f32_e32 v36, 0x3d372713, v32
	v_mul_f32_e32 v36, v32, v36
	v_fma_f32 v36, v32, v36, v32
	v_mul_f32_e32 v36, 0x3f4c422a, v36
	v_mul_f32_e32 v36, -2.0, v36
	v_mul_f32_e32 v36, 0x3fb8aa3b, v36
	v_exp_f32_e32 v36, v36
	s_nop 0
	v_add_f32_e32 v36, 1.0, v36
	v_rcp_f32_e32 v37, v36
	s_nop 0
	v_mul_f32_e32 v32, v32, v37
	v_bfe_u32 v36, v32, 16, 1
	v_add3_u32 v32, v32, v36, s2
	global_store_short_d16_hi v[34:35], v32, off offset:128
	v_add_f32_e32 v32, v59, v71
	v_mul_f32_e32 v34, 0x3d372713, v32
	v_mul_f32_e32 v34, v32, v34
	v_fma_f32 v34, v32, v34, v32
	v_mul_f32_e32 v34, 0x3f4c422a, v34
	v_mul_f32_e32 v34, -2.0, v34
	v_mul_f32_e32 v34, 0x3fb8aa3b, v34
	v_exp_f32_e32 v34, v34
	s_nop 0
	v_add_f32_e32 v34, 1.0, v34
	v_rcp_f32_e32 v35, v34
	s_nop 0
	v_mul_f32_e32 v32, v32, v35
	v_bfe_u32 v34, v32, 16, 1
	v_add3_u32 v32, v32, v34, s2
	v_or_b32_e32 v34, 17, v66
	v_ashrrev_i32_e32 v35, 31, v34
	v_lshlrev_b64 v[34:35], 9, v[34:35]
	v_lshl_add_u64 v[34:35], v[68:69], 0, v[34:35]
	global_store_short_d16_hi v[34:35], v32, off
	v_add_f32_e32 v32, v43, v70
	v_mul_f32_e32 v36, 0x3d372713, v32
	v_mul_f32_e32 v36, v32, v36
	v_fma_f32 v36, v32, v36, v32
	v_mul_f32_e32 v36, 0x3f4c422a, v36
	v_mul_f32_e32 v36, -2.0, v36
	v_mul_f32_e32 v36, 0x3fb8aa3b, v36
	v_exp_f32_e32 v36, v36
	s_nop 0
	v_add_f32_e32 v36, 1.0, v36
	v_rcp_f32_e32 v37, v36
	s_nop 0
	v_mul_f32_e32 v32, v32, v37
	v_bfe_u32 v36, v32, 16, 1
	v_add3_u32 v32, v32, v36, s2
	global_store_short_d16_hi v[34:35], v32, off offset:128
	v_add_f32_e32 v32, v60, v71
	v_mul_f32_e32 v34, 0x3d372713, v32
	v_mul_f32_e32 v34, v32, v34
	v_fma_f32 v34, v32, v34, v32
	v_mul_f32_e32 v34, 0x3f4c422a, v34
	v_mul_f32_e32 v34, -2.0, v34
	v_mul_f32_e32 v34, 0x3fb8aa3b, v34
	v_exp_f32_e32 v34, v34
	s_nop 0
	v_add_f32_e32 v34, 1.0, v34
	v_rcp_f32_e32 v35, v34
	s_nop 0
	v_mul_f32_e32 v32, v32, v35
	v_bfe_u32 v34, v32, 16, 1
	v_add3_u32 v32, v32, v34, s2
	v_or_b32_e32 v34, 18, v66
	v_ashrrev_i32_e32 v35, 31, v34
	v_lshlrev_b64 v[34:35], 9, v[34:35]
	v_lshl_add_u64 v[34:35], v[68:69], 0, v[34:35]
	global_store_short_d16_hi v[34:35], v32, off
	v_add_f32_e32 v32, v44, v70
	v_mul_f32_e32 v36, 0x3d372713, v32
	v_mul_f32_e32 v36, v32, v36
	v_fma_f32 v36, v32, v36, v32
	v_mul_f32_e32 v36, 0x3f4c422a, v36
	v_mul_f32_e32 v36, -2.0, v36
	v_mul_f32_e32 v36, 0x3fb8aa3b, v36
	v_exp_f32_e32 v36, v36
	s_nop 0
	v_add_f32_e32 v36, 1.0, v36
	v_rcp_f32_e32 v37, v36
	s_nop 0
	v_mul_f32_e32 v32, v32, v37
	v_bfe_u32 v36, v32, 16, 1
	v_add3_u32 v32, v32, v36, s2
	global_store_short_d16_hi v[34:35], v32, off offset:128
	v_add_f32_e32 v32, v61, v71
	v_mul_f32_e32 v34, 0x3d372713, v32
	v_mul_f32_e32 v34, v32, v34
	v_fma_f32 v34, v32, v34, v32
	v_mul_f32_e32 v34, 0x3f4c422a, v34
	v_mul_f32_e32 v34, -2.0, v34
	v_mul_f32_e32 v34, 0x3fb8aa3b, v34
	v_exp_f32_e32 v34, v34
	s_nop 0
	v_add_f32_e32 v34, 1.0, v34
	v_rcp_f32_e32 v35, v34
	s_nop 0
	v_mul_f32_e32 v32, v32, v35
	v_bfe_u32 v34, v32, 16, 1
	v_add3_u32 v32, v32, v34, s2
	v_or_b32_e32 v34, 19, v66
	v_ashrrev_i32_e32 v35, 31, v34
	v_lshlrev_b64 v[34:35], 9, v[34:35]
	v_lshl_add_u64 v[34:35], v[68:69], 0, v[34:35]
	global_store_short_d16_hi v[34:35], v32, off
	v_add_f32_e32 v32, v45, v70
	v_mul_f32_e32 v36, 0x3d372713, v32
	v_mul_f32_e32 v36, v32, v36
	v_fma_f32 v36, v32, v36, v32
	v_mul_f32_e32 v36, 0x3f4c422a, v36
	v_mul_f32_e32 v36, -2.0, v36
	v_mul_f32_e32 v36, 0x3fb8aa3b, v36
	v_exp_f32_e32 v36, v36
	s_nop 0
	v_add_f32_e32 v36, 1.0, v36
	v_rcp_f32_e32 v37, v36
	s_nop 0
	v_mul_f32_e32 v32, v32, v37
	v_bfe_u32 v36, v32, 16, 1
	v_add3_u32 v32, v32, v36, s2
	global_store_short_d16_hi v[34:35], v32, off offset:128
	v_add_f32_e32 v32, v62, v71
	v_mul_f32_e32 v35, 0x3d372713, v32
	v_mul_f32_e32 v35, v32, v35
	v_fma_f32 v35, v32, v35, v32
	v_mul_f32_e32 v35, 0x3f4c422a, v35
	v_mul_f32_e32 v35, -2.0, v35
	v_mul_f32_e32 v35, 0x3fb8aa3b, v35
	v_exp_f32_e32 v35, v35
	v_or_b32_e32 v34, 24, v66
	v_add_f32_e32 v35, 1.0, v35
	v_rcp_f32_e32 v36, v35
	s_nop 0
	v_mul_f32_e32 v32, v32, v36
	v_bfe_u32 v35, v32, 16, 1
	v_add3_u32 v32, v32, v35, s2
	v_ashrrev_i32_e32 v35, 31, v34
	v_lshlrev_b64 v[34:35], 9, v[34:35]
	v_lshl_add_u64 v[34:35], v[68:69], 0, v[34:35]
	global_store_short_d16_hi v[34:35], v32, off
	v_add_f32_e32 v32, v46, v70
	v_mul_f32_e32 v36, 0x3d372713, v32
	v_mul_f32_e32 v36, v32, v36
	v_fma_f32 v36, v32, v36, v32
	v_mul_f32_e32 v36, 0x3f4c422a, v36
	v_mul_f32_e32 v36, -2.0, v36
	v_mul_f32_e32 v36, 0x3fb8aa3b, v36
	v_exp_f32_e32 v36, v36
	s_nop 0
	v_add_f32_e32 v36, 1.0, v36
	v_rcp_f32_e32 v37, v36
	s_nop 0
	v_mul_f32_e32 v32, v32, v37
	v_bfe_u32 v36, v32, 16, 1
	v_add3_u32 v32, v32, v36, s2
	global_store_short_d16_hi v[34:35], v32, off offset:128
	v_add_f32_e32 v32, v63, v71
	v_mul_f32_e32 v34, 0x3d372713, v32
	v_mul_f32_e32 v34, v32, v34
	v_fma_f32 v34, v32, v34, v32
	v_mul_f32_e32 v34, 0x3f4c422a, v34
	v_mul_f32_e32 v34, -2.0, v34
	v_mul_f32_e32 v34, 0x3fb8aa3b, v34
	v_exp_f32_e32 v34, v34
	s_nop 0
	v_add_f32_e32 v34, 1.0, v34
	v_rcp_f32_e32 v35, v34
	s_nop 0
	v_mul_f32_e32 v32, v32, v35
	v_bfe_u32 v34, v32, 16, 1
	v_add3_u32 v32, v32, v34, s2
	v_or_b32_e32 v34, 25, v66
	v_ashrrev_i32_e32 v35, 31, v34
	v_lshlrev_b64 v[34:35], 9, v[34:35]
	v_lshl_add_u64 v[34:35], v[68:69], 0, v[34:35]
	global_store_short_d16_hi v[34:35], v32, off
	v_add_f32_e32 v32, v47, v70
	v_mul_f32_e32 v36, 0x3d372713, v32
	v_mul_f32_e32 v36, v32, v36
	v_fma_f32 v36, v32, v36, v32
	v_mul_f32_e32 v36, 0x3f4c422a, v36
	v_mul_f32_e32 v36, -2.0, v36
	v_mul_f32_e32 v36, 0x3fb8aa3b, v36
	v_exp_f32_e32 v36, v36
	s_nop 0
	v_add_f32_e32 v36, 1.0, v36
	v_rcp_f32_e32 v37, v36
	s_nop 0
	v_mul_f32_e32 v32, v32, v37
	v_bfe_u32 v36, v32, 16, 1
	v_add3_u32 v32, v32, v36, s2
	global_store_short_d16_hi v[34:35], v32, off offset:128
	v_add_f32_e32 v32, v64, v71
	v_mul_f32_e32 v34, 0x3d372713, v32
	v_mul_f32_e32 v34, v32, v34
	v_fma_f32 v34, v32, v34, v32
	v_mul_f32_e32 v34, 0x3f4c422a, v34
	v_mul_f32_e32 v34, -2.0, v34
	v_mul_f32_e32 v34, 0x3fb8aa3b, v34
	v_exp_f32_e32 v34, v34
	s_nop 0
	v_add_f32_e32 v34, 1.0, v34
	v_rcp_f32_e32 v35, v34
	s_nop 0
	v_mul_f32_e32 v32, v32, v35
	v_bfe_u32 v34, v32, 16, 1
	v_add3_u32 v32, v32, v34, s2
	v_or_b32_e32 v34, 26, v66
	v_ashrrev_i32_e32 v35, 31, v34
	v_lshlrev_b64 v[34:35], 9, v[34:35]
	v_lshl_add_u64 v[34:35], v[68:69], 0, v[34:35]
	global_store_short_d16_hi v[34:35], v32, off
	v_add_f32_e32 v32, v48, v70
	v_mul_f32_e32 v36, 0x3d372713, v32
	v_mul_f32_e32 v36, v32, v36
	v_fma_f32 v36, v32, v36, v32
	v_mul_f32_e32 v36, 0x3f4c422a, v36
	v_mul_f32_e32 v36, -2.0, v36
	v_mul_f32_e32 v36, 0x3fb8aa3b, v36
	v_exp_f32_e32 v36, v36
	s_nop 0
	v_add_f32_e32 v36, 1.0, v36
	v_rcp_f32_e32 v37, v36
	s_nop 0
	v_mul_f32_e32 v32, v32, v37
	v_bfe_u32 v36, v32, 16, 1
	v_add3_u32 v32, v32, v36, s2
	global_store_short_d16_hi v[34:35], v32, off offset:128
	v_add_f32_e32 v32, v65, v71
	v_mul_f32_e32 v34, 0x3d372713, v32
	v_mul_f32_e32 v34, v32, v34
	v_fma_f32 v34, v32, v34, v32
	v_mul_f32_e32 v34, 0x3f4c422a, v34
	v_mul_f32_e32 v34, -2.0, v34
	v_mul_f32_e32 v34, 0x3fb8aa3b, v34
	v_exp_f32_e32 v34, v34
	s_nop 0
	v_add_f32_e32 v34, 1.0, v34
	v_rcp_f32_e32 v35, v34
	s_nop 0
	v_mul_f32_e32 v32, v32, v35
	v_bfe_u32 v34, v32, 16, 1
	v_add3_u32 v32, v32, v34, s2
	v_or_b32_e32 v34, 27, v66
	v_ashrrev_i32_e32 v35, 31, v34
	v_lshlrev_b64 v[34:35], 9, v[34:35]
	v_lshl_add_u64 v[34:35], v[68:69], 0, v[34:35]
	global_store_short_d16_hi v[34:35], v32, off
	v_add_f32_e32 v32, v49, v70
	v_mul_f32_e32 v36, 0x3d372713, v32
	v_mul_f32_e32 v36, v32, v36
	v_fma_f32 v36, v32, v36, v32
	v_mul_f32_e32 v36, 0x3f4c422a, v36
	v_mul_f32_e32 v36, -2.0, v36
	v_mul_f32_e32 v36, 0x3fb8aa3b, v36
	v_exp_f32_e32 v36, v36
	s_nop 0
	v_add_f32_e32 v36, 1.0, v36
	v_rcp_f32_e32 v37, v36
	s_nop 0
	v_mul_f32_e32 v32, v32, v37
	v_bfe_u32 v36, v32, 16, 1
	v_add3_u32 v32, v32, v36, s2
	global_store_short_d16_hi v[34:35], v32, off offset:128
	v_mul_f32_e32 v32, 0x3d372713, v16
	v_mul_f32_e32 v32, v16, v32
	v_fma_f32 v32, v16, v32, v16
	v_mul_f32_e32 v32, 0x3f4c422a, v32
	v_mul_f32_e32 v32, -2.0, v32
	v_mul_f32_e32 v32, 0x3fb8aa3b, v32
	v_exp_f32_e32 v32, v32
	v_or_b32_e32 v34, 32, v66
	v_add_f32_e32 v32, 1.0, v32
	v_rcp_f32_e32 v35, v32
	s_nop 0
	v_mul_f32_e32 v16, v16, v35
	v_ashrrev_i32_e32 v35, 31, v34
	v_bfe_u32 v32, v16, 16, 1
	v_lshlrev_b64 v[34:35], 9, v[34:35]
	v_add3_u32 v16, v16, v32, s2
	v_lshl_add_u64 v[34:35], v[68:69], 0, v[34:35]
	global_store_short_d16_hi v[34:35], v16, off
	v_mul_f32_e32 v16, 0x3d372713, v0
	v_mul_f32_e32 v16, v0, v16
	v_fma_f32 v16, v0, v16, v0
	v_mul_f32_e32 v16, 0x3f4c422a, v16
	v_mul_f32_e32 v16, -2.0, v16
	v_mul_f32_e32 v16, 0x3fb8aa3b, v16
	v_exp_f32_e32 v16, v16
	s_nop 0
	v_add_f32_e32 v16, 1.0, v16
	v_rcp_f32_e32 v32, v16
	s_nop 0
	v_mul_f32_e32 v0, v0, v32
	v_bfe_u32 v16, v0, 16, 1
	v_add3_u32 v0, v0, v16, s2
	global_store_short_d16_hi v[34:35], v0, off offset:128
	v_add_f32_e32 v0, v17, v71
	v_mul_f32_e32 v16, 0x3d372713, v0
	v_mul_f32_e32 v16, v0, v16
	v_fma_f32 v16, v0, v16, v0
	v_mul_f32_e32 v16, 0x3f4c422a, v16
	v_mul_f32_e32 v16, -2.0, v16
	v_mul_f32_e32 v16, 0x3fb8aa3b, v16
	v_exp_f32_e32 v16, v16
	s_nop 0
	v_add_f32_e32 v16, 1.0, v16
	v_rcp_f32_e32 v17, v16
	s_nop 0
	v_mul_f32_e32 v0, v0, v17
	v_bfe_u32 v16, v0, 16, 1
	v_add3_u32 v0, v0, v16, s2
	v_or_b32_e32 v16, 33, v66
	v_ashrrev_i32_e32 v17, 31, v16
	v_lshlrev_b64 v[16:17], 9, v[16:17]
	v_lshl_add_u64 v[16:17], v[68:69], 0, v[16:17]
	global_store_short_d16_hi v[16:17], v0, off
	v_add_f32_e32 v0, v1, v70
	v_mul_f32_e32 v1, 0x3d372713, v0
	v_mul_f32_e32 v1, v0, v1
	v_fma_f32 v1, v0, v1, v0
	v_mul_f32_e32 v1, 0x3f4c422a, v1
	v_mul_f32_e32 v1, -2.0, v1
	v_mul_f32_e32 v1, 0x3fb8aa3b, v1
	v_exp_f32_e32 v1, v1
	s_nop 0
	v_add_f32_e32 v1, 1.0, v1
	v_rcp_f32_e32 v32, v1
	s_nop 0
	v_mul_f32_e32 v0, v0, v32
	v_bfe_u32 v1, v0, 16, 1
	v_add3_u32 v0, v0, v1, s2
	global_store_short_d16_hi v[16:17], v0, off offset:128
	v_add_f32_e32 v0, v18, v71
	v_mul_f32_e32 v1, 0x3d372713, v0
	v_mul_f32_e32 v1, v0, v1
	v_fma_f32 v1, v0, v1, v0
	v_mul_f32_e32 v1, 0x3f4c422a, v1
	v_mul_f32_e32 v1, -2.0, v1
	v_mul_f32_e32 v1, 0x3fb8aa3b, v1
	v_exp_f32_e32 v1, v1
	s_nop 0
	v_add_f32_e32 v1, 1.0, v1
	v_rcp_f32_e32 v16, v1
	s_nop 0
	v_mul_f32_e32 v0, v0, v16
	v_bfe_u32 v1, v0, 16, 1
	v_add3_u32 v16, v0, v1, s2
	v_or_b32_e32 v0, 34, v66
	v_ashrrev_i32_e32 v1, 31, v0
	v_lshlrev_b64 v[0:1], 9, v[0:1]
	v_lshl_add_u64 v[0:1], v[68:69], 0, v[0:1]
	global_store_short_d16_hi v[0:1], v16, off
	v_mul_f32_e32 v16, 0x3d372713, v2
	v_mul_f32_e32 v16, v2, v16
	v_fma_f32 v16, v2, v16, v2
	v_mul_f32_e32 v16, 0x3f4c422a, v16
	v_mul_f32_e32 v16, -2.0, v16
	v_mul_f32_e32 v16, 0x3fb8aa3b, v16
	v_exp_f32_e32 v16, v16
	s_nop 0
	v_add_f32_e32 v16, 1.0, v16
	v_rcp_f32_e32 v17, v16
	s_nop 0
	v_mul_f32_e32 v2, v2, v17
	v_bfe_u32 v16, v2, 16, 1
	v_add3_u32 v2, v2, v16, s2
	global_store_short_d16_hi v[0:1], v2, off offset:128
	v_add_f32_e32 v0, v19, v71
	v_mul_f32_e32 v1, 0x3d372713, v0
	v_mul_f32_e32 v1, v0, v1
	v_fma_f32 v1, v0, v1, v0
	v_mul_f32_e32 v1, 0x3f4c422a, v1
	v_mul_f32_e32 v1, -2.0, v1
	v_mul_f32_e32 v1, 0x3fb8aa3b, v1
	v_exp_f32_e32 v1, v1
	s_nop 0
	v_add_f32_e32 v1, 1.0, v1
	v_rcp_f32_e32 v2, v1
	s_nop 0
	v_mul_f32_e32 v0, v0, v2
	v_bfe_u32 v1, v0, 16, 1
	v_add3_u32 v2, v0, v1, s2
	v_or_b32_e32 v0, 35, v66
	v_ashrrev_i32_e32 v1, 31, v0
	v_lshlrev_b64 v[0:1], 9, v[0:1]
	v_lshl_add_u64 v[0:1], v[68:69], 0, v[0:1]
	global_store_short_d16_hi v[0:1], v2, off
	v_add_f32_e32 v2, v3, v70
	v_mul_f32_e32 v3, 0x3d372713, v2
	v_mul_f32_e32 v3, v2, v3
	v_fma_f32 v3, v2, v3, v2
	v_mul_f32_e32 v3, 0x3f4c422a, v3
	v_mul_f32_e32 v3, -2.0, v3
	v_mul_f32_e32 v3, 0x3fb8aa3b, v3
	v_exp_f32_e32 v3, v3
	s_nop 0
	v_add_f32_e32 v3, 1.0, v3
	v_rcp_f32_e32 v16, v3
	s_nop 0
	v_mul_f32_e32 v2, v2, v16
	v_bfe_u32 v3, v2, 16, 1
	v_add3_u32 v2, v2, v3, s2
	global_store_short_d16_hi v[0:1], v2, off offset:128
	v_add_f32_e32 v1, v20, v71
	v_mul_f32_e32 v2, 0x3d372713, v1
	v_mul_f32_e32 v2, v1, v2
	v_fma_f32 v2, v1, v2, v1
	v_mul_f32_e32 v2, 0x3f4c422a, v2
	v_mul_f32_e32 v2, -2.0, v2
	v_mul_f32_e32 v2, 0x3fb8aa3b, v2
	v_exp_f32_e32 v2, v2
	v_or_b32_e32 v0, 40, v66
	v_add_f32_e32 v2, 1.0, v2
	v_rcp_f32_e32 v3, v2
	s_nop 0
	v_mul_f32_e32 v1, v1, v3
	v_bfe_u32 v2, v1, 16, 1
	v_add3_u32 v2, v1, v2, s2
	v_ashrrev_i32_e32 v1, 31, v0
	v_lshlrev_b64 v[0:1], 9, v[0:1]
	v_lshl_add_u64 v[0:1], v[68:69], 0, v[0:1]
	global_store_short_d16_hi v[0:1], v2, off
	v_add_f32_e32 v2, v4, v70
	v_mul_f32_e32 v3, 0x3d372713, v2
	v_mul_f32_e32 v3, v2, v3
	v_fma_f32 v3, v2, v3, v2
	v_mul_f32_e32 v3, 0x3f4c422a, v3
	v_mul_f32_e32 v3, -2.0, v3
	v_mul_f32_e32 v3, 0x3fb8aa3b, v3
	v_exp_f32_e32 v3, v3
	s_nop 0
	v_add_f32_e32 v3, 1.0, v3
	v_rcp_f32_e32 v4, v3
	s_nop 0
	v_mul_f32_e32 v2, v2, v4
	v_bfe_u32 v3, v2, 16, 1
	v_add3_u32 v2, v2, v3, s2
	global_store_short_d16_hi v[0:1], v2, off offset:128
	v_add_f32_e32 v0, v21, v71
	v_mul_f32_e32 v1, 0x3d372713, v0
	v_mul_f32_e32 v1, v0, v1
	v_fma_f32 v1, v0, v1, v0
	v_mul_f32_e32 v1, 0x3f4c422a, v1
	v_mul_f32_e32 v1, -2.0, v1
	v_mul_f32_e32 v1, 0x3fb8aa3b, v1
	v_exp_f32_e32 v1, v1
	s_nop 0
	v_add_f32_e32 v1, 1.0, v1
	v_rcp_f32_e32 v2, v1
	s_nop 0
	v_mul_f32_e32 v0, v0, v2
	v_bfe_u32 v1, v0, 16, 1
	v_add3_u32 v2, v0, v1, s2
	v_or_b32_e32 v0, 41, v66
	v_ashrrev_i32_e32 v1, 31, v0
	v_lshlrev_b64 v[0:1], 9, v[0:1]
	v_lshl_add_u64 v[0:1], v[68:69], 0, v[0:1]
	global_store_short_d16_hi v[0:1], v2, off
	v_add_f32_e32 v2, v5, v70
	v_mul_f32_e32 v3, 0x3d372713, v2
	v_mul_f32_e32 v3, v2, v3
	v_fma_f32 v3, v2, v3, v2
	v_mul_f32_e32 v3, 0x3f4c422a, v3
	v_mul_f32_e32 v3, -2.0, v3
	v_mul_f32_e32 v3, 0x3fb8aa3b, v3
	v_exp_f32_e32 v3, v3
	s_nop 0
	v_add_f32_e32 v3, 1.0, v3
	v_rcp_f32_e32 v4, v3
	s_nop 0
	v_mul_f32_e32 v2, v2, v4
	v_bfe_u32 v3, v2, 16, 1
	v_add3_u32 v2, v2, v3, s2
	global_store_short_d16_hi v[0:1], v2, off offset:128
	v_add_f32_e32 v0, v22, v71
	v_mul_f32_e32 v1, 0x3d372713, v0
	v_mul_f32_e32 v1, v0, v1
	v_fma_f32 v1, v0, v1, v0
	v_mul_f32_e32 v1, 0x3f4c422a, v1
	v_mul_f32_e32 v1, -2.0, v1
	v_mul_f32_e32 v1, 0x3fb8aa3b, v1
	v_exp_f32_e32 v1, v1
	s_nop 0
	v_add_f32_e32 v1, 1.0, v1
	v_rcp_f32_e32 v2, v1
	s_nop 0
	v_mul_f32_e32 v0, v0, v2
	v_bfe_u32 v1, v0, 16, 1
	v_add3_u32 v2, v0, v1, s2
	v_or_b32_e32 v0, 42, v66
	v_ashrrev_i32_e32 v1, 31, v0
	v_lshlrev_b64 v[0:1], 9, v[0:1]
	v_lshl_add_u64 v[0:1], v[68:69], 0, v[0:1]
	global_store_short_d16_hi v[0:1], v2, off
	v_add_f32_e32 v2, v6, v70
	v_mul_f32_e32 v3, 0x3d372713, v2
	v_mul_f32_e32 v3, v2, v3
	v_fma_f32 v3, v2, v3, v2
	v_mul_f32_e32 v3, 0x3f4c422a, v3
	v_mul_f32_e32 v3, -2.0, v3
	v_mul_f32_e32 v3, 0x3fb8aa3b, v3
	v_exp_f32_e32 v3, v3
	s_nop 0
	v_add_f32_e32 v3, 1.0, v3
	v_rcp_f32_e32 v4, v3
	s_nop 0
	v_mul_f32_e32 v2, v2, v4
	v_bfe_u32 v3, v2, 16, 1
	v_add3_u32 v2, v2, v3, s2
	global_store_short_d16_hi v[0:1], v2, off offset:128
	v_add_f32_e32 v0, v23, v71
	v_mul_f32_e32 v1, 0x3d372713, v0
	v_mul_f32_e32 v1, v0, v1
	v_fma_f32 v1, v0, v1, v0
	v_mul_f32_e32 v1, 0x3f4c422a, v1
	v_mul_f32_e32 v1, -2.0, v1
	v_mul_f32_e32 v1, 0x3fb8aa3b, v1
	v_exp_f32_e32 v1, v1
	s_nop 0
	v_add_f32_e32 v1, 1.0, v1
	v_rcp_f32_e32 v2, v1
	s_nop 0
	v_mul_f32_e32 v0, v0, v2
	v_bfe_u32 v1, v0, 16, 1
	v_add3_u32 v2, v0, v1, s2
	v_or_b32_e32 v0, 43, v66
	v_ashrrev_i32_e32 v1, 31, v0
	v_lshlrev_b64 v[0:1], 9, v[0:1]
	v_lshl_add_u64 v[0:1], v[68:69], 0, v[0:1]
	global_store_short_d16_hi v[0:1], v2, off
	v_add_f32_e32 v2, v7, v70
	v_mul_f32_e32 v3, 0x3d372713, v2
	v_mul_f32_e32 v3, v2, v3
	v_fma_f32 v3, v2, v3, v2
	v_mul_f32_e32 v3, 0x3f4c422a, v3
	v_mul_f32_e32 v3, -2.0, v3
	v_mul_f32_e32 v3, 0x3fb8aa3b, v3
	v_exp_f32_e32 v3, v3
	s_nop 0
	v_add_f32_e32 v3, 1.0, v3
	v_rcp_f32_e32 v4, v3
	s_nop 0
	v_mul_f32_e32 v2, v2, v4
	v_bfe_u32 v3, v2, 16, 1
	v_add3_u32 v2, v2, v3, s2
	global_store_short_d16_hi v[0:1], v2, off offset:128
	v_add_f32_e32 v1, v24, v71
	v_mul_f32_e32 v2, 0x3d372713, v1
	v_mul_f32_e32 v2, v1, v2
	v_fma_f32 v2, v1, v2, v1
	v_mul_f32_e32 v2, 0x3f4c422a, v2
	v_mul_f32_e32 v2, -2.0, v2
	v_mul_f32_e32 v2, 0x3fb8aa3b, v2
	v_exp_f32_e32 v2, v2
	v_or_b32_e32 v0, 48, v66
	v_add_f32_e32 v2, 1.0, v2
	v_rcp_f32_e32 v3, v2
	s_nop 0
	v_mul_f32_e32 v1, v1, v3
	v_bfe_u32 v2, v1, 16, 1
	v_add3_u32 v2, v1, v2, s2
	v_ashrrev_i32_e32 v1, 31, v0
	v_lshlrev_b64 v[0:1], 9, v[0:1]
	v_lshl_add_u64 v[0:1], v[68:69], 0, v[0:1]
	global_store_short_d16_hi v[0:1], v2, off
	v_add_f32_e32 v2, v8, v70
	v_mul_f32_e32 v3, 0x3d372713, v2
	v_mul_f32_e32 v3, v2, v3
	v_fma_f32 v3, v2, v3, v2
	v_mul_f32_e32 v3, 0x3f4c422a, v3
	v_mul_f32_e32 v3, -2.0, v3
	v_mul_f32_e32 v3, 0x3fb8aa3b, v3
	v_exp_f32_e32 v3, v3
	s_nop 0
	v_add_f32_e32 v3, 1.0, v3
	v_rcp_f32_e32 v4, v3
	s_nop 0
	v_mul_f32_e32 v2, v2, v4
	v_bfe_u32 v3, v2, 16, 1
	v_add3_u32 v2, v2, v3, s2
	global_store_short_d16_hi v[0:1], v2, off offset:128
	v_add_f32_e32 v0, v25, v71
	v_mul_f32_e32 v1, 0x3d372713, v0
	v_mul_f32_e32 v1, v0, v1
	v_fma_f32 v1, v0, v1, v0
	v_mul_f32_e32 v1, 0x3f4c422a, v1
	v_mul_f32_e32 v1, -2.0, v1
	v_mul_f32_e32 v1, 0x3fb8aa3b, v1
	v_exp_f32_e32 v1, v1
	s_nop 0
	v_add_f32_e32 v1, 1.0, v1
	v_rcp_f32_e32 v2, v1
	s_nop 0
	v_mul_f32_e32 v0, v0, v2
	v_bfe_u32 v1, v0, 16, 1
	v_add3_u32 v2, v0, v1, s2
	v_or_b32_e32 v0, 49, v66
	v_ashrrev_i32_e32 v1, 31, v0
	v_lshlrev_b64 v[0:1], 9, v[0:1]
	v_lshl_add_u64 v[0:1], v[68:69], 0, v[0:1]
	global_store_short_d16_hi v[0:1], v2, off
	v_add_f32_e32 v2, v9, v70
	v_mul_f32_e32 v3, 0x3d372713, v2
	v_mul_f32_e32 v3, v2, v3
	v_fma_f32 v3, v2, v3, v2
	v_mul_f32_e32 v3, 0x3f4c422a, v3
	v_mul_f32_e32 v3, -2.0, v3
	v_mul_f32_e32 v3, 0x3fb8aa3b, v3
	v_exp_f32_e32 v3, v3
	s_nop 0
	v_add_f32_e32 v3, 1.0, v3
	v_rcp_f32_e32 v4, v3
	s_nop 0
	v_mul_f32_e32 v2, v2, v4
	v_bfe_u32 v3, v2, 16, 1
	v_add3_u32 v2, v2, v3, s2
	global_store_short_d16_hi v[0:1], v2, off offset:128
	v_add_f32_e32 v0, v26, v71
	v_mul_f32_e32 v1, 0x3d372713, v0
	v_mul_f32_e32 v1, v0, v1
	v_fma_f32 v1, v0, v1, v0
	v_mul_f32_e32 v1, 0x3f4c422a, v1
	v_mul_f32_e32 v1, -2.0, v1
	v_mul_f32_e32 v1, 0x3fb8aa3b, v1
	v_exp_f32_e32 v1, v1
	s_nop 0
	v_add_f32_e32 v1, 1.0, v1
	v_rcp_f32_e32 v2, v1
	s_nop 0
	v_mul_f32_e32 v0, v0, v2
	v_bfe_u32 v1, v0, 16, 1
	v_add3_u32 v2, v0, v1, s2
	v_or_b32_e32 v0, 50, v66
	v_ashrrev_i32_e32 v1, 31, v0
	v_lshlrev_b64 v[0:1], 9, v[0:1]
	v_lshl_add_u64 v[0:1], v[68:69], 0, v[0:1]
	global_store_short_d16_hi v[0:1], v2, off
	v_add_f32_e32 v2, v10, v70
	v_mul_f32_e32 v3, 0x3d372713, v2
	v_mul_f32_e32 v3, v2, v3
	v_fma_f32 v3, v2, v3, v2
	v_mul_f32_e32 v3, 0x3f4c422a, v3
	v_mul_f32_e32 v3, -2.0, v3
	v_mul_f32_e32 v3, 0x3fb8aa3b, v3
	v_exp_f32_e32 v3, v3
	s_nop 0
	v_add_f32_e32 v3, 1.0, v3
	v_rcp_f32_e32 v4, v3
	s_nop 0
	v_mul_f32_e32 v2, v2, v4
	v_bfe_u32 v3, v2, 16, 1
	v_add3_u32 v2, v2, v3, s2
	global_store_short_d16_hi v[0:1], v2, off offset:128
	v_add_f32_e32 v0, v27, v71
	v_mul_f32_e32 v1, 0x3d372713, v0
	v_mul_f32_e32 v1, v0, v1
	v_fma_f32 v1, v0, v1, v0
	v_mul_f32_e32 v1, 0x3f4c422a, v1
	v_mul_f32_e32 v1, -2.0, v1
	v_mul_f32_e32 v1, 0x3fb8aa3b, v1
	v_exp_f32_e32 v1, v1
	s_nop 0
	v_add_f32_e32 v1, 1.0, v1
	v_rcp_f32_e32 v2, v1
	s_nop 0
	v_mul_f32_e32 v0, v0, v2
	v_bfe_u32 v1, v0, 16, 1
	v_add3_u32 v2, v0, v1, s2
	v_or_b32_e32 v0, 51, v66
	v_ashrrev_i32_e32 v1, 31, v0
	v_lshlrev_b64 v[0:1], 9, v[0:1]
	v_lshl_add_u64 v[0:1], v[68:69], 0, v[0:1]
	global_store_short_d16_hi v[0:1], v2, off
	v_add_f32_e32 v2, v11, v70
	v_mul_f32_e32 v3, 0x3d372713, v2
	v_mul_f32_e32 v3, v2, v3
	v_fma_f32 v3, v2, v3, v2
	v_mul_f32_e32 v3, 0x3f4c422a, v3
	v_mul_f32_e32 v3, -2.0, v3
	v_mul_f32_e32 v3, 0x3fb8aa3b, v3
	v_exp_f32_e32 v3, v3
	s_nop 0
	v_add_f32_e32 v3, 1.0, v3
	v_rcp_f32_e32 v4, v3
	s_nop 0
	v_mul_f32_e32 v2, v2, v4
	v_bfe_u32 v3, v2, 16, 1
	v_add3_u32 v2, v2, v3, s2
	global_store_short_d16_hi v[0:1], v2, off offset:128
	v_add_f32_e32 v1, v28, v71
	v_mul_f32_e32 v2, 0x3d372713, v1
	v_mul_f32_e32 v2, v1, v2
	v_fma_f32 v2, v1, v2, v1
	v_mul_f32_e32 v2, 0x3f4c422a, v2
	v_mul_f32_e32 v2, -2.0, v2
	v_mul_f32_e32 v2, 0x3fb8aa3b, v2
	v_exp_f32_e32 v2, v2
	v_or_b32_e32 v0, 56, v66
	v_add_f32_e32 v2, 1.0, v2
	v_rcp_f32_e32 v3, v2
	s_nop 0
	v_mul_f32_e32 v1, v1, v3
	v_bfe_u32 v2, v1, 16, 1
	v_add3_u32 v2, v1, v2, s2
	v_ashrrev_i32_e32 v1, 31, v0
	v_lshlrev_b64 v[0:1], 9, v[0:1]
	v_lshl_add_u64 v[0:1], v[68:69], 0, v[0:1]
	global_store_short_d16_hi v[0:1], v2, off
	v_add_f32_e32 v2, v12, v70
	v_mul_f32_e32 v3, 0x3d372713, v2
	v_mul_f32_e32 v3, v2, v3
	v_fma_f32 v3, v2, v3, v2
	v_mul_f32_e32 v3, 0x3f4c422a, v3
	v_mul_f32_e32 v3, -2.0, v3
	v_mul_f32_e32 v3, 0x3fb8aa3b, v3
	v_exp_f32_e32 v3, v3
	s_nop 0
	v_add_f32_e32 v3, 1.0, v3
	v_rcp_f32_e32 v4, v3
	s_nop 0
	v_mul_f32_e32 v2, v2, v4
	v_bfe_u32 v3, v2, 16, 1
	v_add3_u32 v2, v2, v3, s2
	global_store_short_d16_hi v[0:1], v2, off offset:128
	v_add_f32_e32 v0, v29, v71
	v_mul_f32_e32 v1, 0x3d372713, v0
	v_mul_f32_e32 v1, v0, v1
	v_fma_f32 v1, v0, v1, v0
	v_mul_f32_e32 v1, 0x3f4c422a, v1
	v_mul_f32_e32 v1, -2.0, v1
	v_mul_f32_e32 v1, 0x3fb8aa3b, v1
	v_exp_f32_e32 v1, v1
	s_nop 0
	v_add_f32_e32 v1, 1.0, v1
	v_rcp_f32_e32 v2, v1
	s_nop 0
	v_mul_f32_e32 v0, v0, v2
	v_bfe_u32 v1, v0, 16, 1
	v_add3_u32 v2, v0, v1, s2
	v_or_b32_e32 v0, 57, v66
	v_ashrrev_i32_e32 v1, 31, v0
	v_lshlrev_b64 v[0:1], 9, v[0:1]
	v_lshl_add_u64 v[0:1], v[68:69], 0, v[0:1]
	global_store_short_d16_hi v[0:1], v2, off
	v_add_f32_e32 v2, v13, v70
	v_mul_f32_e32 v3, 0x3d372713, v2
	v_mul_f32_e32 v3, v2, v3
	v_fma_f32 v3, v2, v3, v2
	v_mul_f32_e32 v3, 0x3f4c422a, v3
	v_mul_f32_e32 v3, -2.0, v3
	v_mul_f32_e32 v3, 0x3fb8aa3b, v3
	v_exp_f32_e32 v3, v3
	s_nop 0
	v_add_f32_e32 v3, 1.0, v3
	v_rcp_f32_e32 v4, v3
	s_nop 0
	v_mul_f32_e32 v2, v2, v4
	v_bfe_u32 v3, v2, 16, 1
	v_add3_u32 v2, v2, v3, s2
	global_store_short_d16_hi v[0:1], v2, off offset:128
	v_add_f32_e32 v0, v30, v71
	v_mul_f32_e32 v1, 0x3d372713, v0
	v_mul_f32_e32 v1, v0, v1
	v_fma_f32 v1, v0, v1, v0
	v_mul_f32_e32 v1, 0x3f4c422a, v1
	v_mul_f32_e32 v1, -2.0, v1
	v_mul_f32_e32 v1, 0x3fb8aa3b, v1
	v_exp_f32_e32 v1, v1
	s_nop 0
	v_add_f32_e32 v1, 1.0, v1
	v_rcp_f32_e32 v2, v1
	s_nop 0
	v_mul_f32_e32 v0, v0, v2
	v_bfe_u32 v1, v0, 16, 1
	v_add3_u32 v2, v0, v1, s2
	v_or_b32_e32 v0, 58, v66
	v_ashrrev_i32_e32 v1, 31, v0
	v_lshlrev_b64 v[0:1], 9, v[0:1]
	v_lshl_add_u64 v[0:1], v[68:69], 0, v[0:1]
	global_store_short_d16_hi v[0:1], v2, off
	v_add_f32_e32 v2, v14, v70
	v_mul_f32_e32 v3, 0x3d372713, v2
	v_mul_f32_e32 v3, v2, v3
	v_fma_f32 v3, v2, v3, v2
	v_mul_f32_e32 v3, 0x3f4c422a, v3
	v_mul_f32_e32 v3, -2.0, v3
	v_mul_f32_e32 v3, 0x3fb8aa3b, v3
	v_exp_f32_e32 v3, v3
	s_nop 0
	v_add_f32_e32 v3, 1.0, v3
	v_rcp_f32_e32 v4, v3
	s_nop 0
	v_mul_f32_e32 v2, v2, v4
	v_bfe_u32 v3, v2, 16, 1
	v_add3_u32 v2, v2, v3, s2
	global_store_short_d16_hi v[0:1], v2, off offset:128
	v_add_f32_e32 v0, v31, v71
	v_mul_f32_e32 v1, 0x3d372713, v0
	v_mul_f32_e32 v1, v0, v1
	v_fma_f32 v1, v0, v1, v0
	v_mul_f32_e32 v1, 0x3f4c422a, v1
	v_mul_f32_e32 v1, -2.0, v1
	v_mul_f32_e32 v1, 0x3fb8aa3b, v1
	v_exp_f32_e32 v1, v1
	s_nop 0
	v_add_f32_e32 v1, 1.0, v1
	v_rcp_f32_e32 v2, v1
	s_nop 0
	v_mul_f32_e32 v0, v0, v2
	v_bfe_u32 v1, v0, 16, 1
	v_add3_u32 v2, v0, v1, s2
	v_or_b32_e32 v0, 59, v66
	v_ashrrev_i32_e32 v1, 31, v0
	v_lshlrev_b64 v[0:1], 9, v[0:1]
	v_lshl_add_u64 v[0:1], v[68:69], 0, v[0:1]
	global_store_short_d16_hi v[0:1], v2, off
	v_add_f32_e32 v2, v15, v70
	v_mul_f32_e32 v3, 0x3d372713, v2
	v_mul_f32_e32 v3, v2, v3
	v_fma_f32 v3, v2, v3, v2
	v_mul_f32_e32 v3, 0x3f4c422a, v3
	v_mul_f32_e32 v3, -2.0, v3
	v_mul_f32_e32 v3, 0x3fb8aa3b, v3
	v_exp_f32_e32 v3, v3
	s_nop 0
	v_add_f32_e32 v3, 1.0, v3
	v_rcp_f32_e32 v4, v3
	s_nop 0
	v_readlane_b32 s0, v251, 24
	s_add_i32 s7, s7, s0
	v_readlane_b32 s0, v251, 26
	v_mul_f32_e32 v2, v2, v4
	v_bfe_u32 v3, v2, 16, 1
	s_add_i32 s6, s6, s0
	v_add3_u32 v2, v2, v3, s2
	s_cmpk_lt_i32 s7, 0x80
	global_store_short_d16_hi v[0:1], v2, off offset:128
	v_readlane_b32 s1, v251, 25
	s_cbranch_scc0 .LBB0_2141
